# v12_hg_m1_rows_once
# baseline (speedup 1.0000x reference)
; #define LAS __attribute__((address_space(3)))
; __device__ __forceinline__ void ld8bf(const bf16_t* p, float (&o)[8]) { unpack8(*(const u32x4*)p, o); }
; __device__ __forceinline__ void w_hg_m1(const Args& a, int l, unsigned char* ws, const bf16_t* proj, LAS unsigned char* wl, int b, int ck_, int h, int lane) {
;     LAS bf16_t* vT = (LAS bf16_t*)wl; LAS bf16_t* kT = (LAS bf16_t*)(wl + TILE_B);
;     const int row0 = b * SEQ + 64 * ck_, lo = lane & 15, fq = lane >> 4;
; #pragma unroll
;     for (int kk = 0; kk < 2; ++kk) { float bb[4][8], r31[8], r63[8], lbv[8];
; #pragma unroll
;         for (int j = 0; j < 8; ++j) lbv[j] = hg_lb(a, l, 64 * h + 32 * kk + 8 * fq + j);
;         const bf16_t* fsrc = proj + (size_t)row0 * NIN + C_HF + 64 * h + 32 * kk + 8 * fq;
;         w_hg_scan(lbv, fsrc, lane, bb, r31, r63);
; #pragma unroll
;         for (int tb = 0; tb < 4; ++tb) { float fp[8]; ld8bf(fsrc + (size_t)(16 * tb + lo) * NIN, fp);
.LBB0_531:
	s_lshr_b32 s20, s90, 8
	s_lshr_b32 s21, s90, 9
	s_add_i32 s20, s20, s90
	s_and_b32 s21, s21, 12
	s_add_i32 s20, s20, s21
	s_and_b32 s20, s20, 15
	s_cmp_lt_u32 s20, 12
	s_cbranch_scc1 .LBB0_530
	v_mov_b32_e32 v33, v144
	s_add_i32 s20, s20, -12
	v_ashrrev_i32_e32 v32, 4, v33
	s_lshl_b32 s34, s20, 6
	v_lshlrev_b32_e32 v0, 3, v32
	v_add_u32_e32 v12, s34, v0
	v_mov_b32_e32 v23, 0
	s_ashr_i32 s21, s90, 31
	s_ashr_i32 s27, s90, 4
	s_lshr_b32 s21, s21, 25
	s_add_i32 s35, s27, s21
	s_ashr_i32 s21, s35, 7
	s_and_b32 s35, s35, 0xffffff80
	s_sub_i32 s27, s27, s35
	s_lshl_b32 s35, s21, 13
	s_lshl_b32 s38, s27, 6
	s_add_i32 s35, s38, s35
	s_mul_hi_i32 s38, s35, 0x1800
	s_mulk_i32 s35, 0x1800
	s_add_u32 s91, s8, s35
	s_addc_u32 s92, s9, s38
	s_lshl_b32 s93, s34, 1
	s_add_i32 s38, s93, 0x1200
	v_and_b32_e32 v196, 15, v33
	v_lshrrev_b32_e32 v197, 4, v33
	v_mul_u32_u24_e32 v196, 0x1800, v196
	v_lshl_add_u32 v196, v197, 4, v196
	v_add_u32_e32 v196, s38, v196
	v_add_co_u32_e32 v198, vcc, s91, v196
	v_mov_b32_e32 v199, s92
	s_nop 0
	v_addc_co_u32_e32 v199, vcc, 0, v199, vcc
	global_load_dwordx4 v[222:225], v[198:199], off
	global_load_dwordx4 v[238:241], v[198:199], off offset:64
	v_add_u32_e32 v196, 0x18000, v196
	v_add_co_u32_e32 v198, vcc, s91, v196
	v_mov_b32_e32 v199, s92
	s_nop 0
	v_addc_co_u32_e32 v199, vcc, 0, v199, vcc
	global_load_dwordx4 v[226:229], v[198:199], off
	global_load_dwordx4 v[242:245], v[198:199], off offset:64
	v_add_u32_e32 v196, 0x18000, v196
	v_add_co_u32_e32 v198, vcc, s91, v196
	v_mov_b32_e32 v199, s92
	s_nop 0
	v_addc_co_u32_e32 v199, vcc, 0, v199, vcc
	global_load_dwordx4 v[230:233], v[198:199], off
	global_load_dwordx4 v[246:249], v[198:199], off offset:64
	v_add_u32_e32 v196, 0x18000, v196
	v_add_co_u32_e32 v198, vcc, s91, v196
	v_mov_b32_e32 v199, s92
	s_nop 0
	v_addc_co_u32_e32 v199, vcc, 0, v199, vcc
	global_load_dwordx4 v[234:237], v[198:199], off
	global_load_dwordx4 v[250:253], v[198:199], off offset:64
	s_and_b64 vcc, exec, s[36:37]
	v_ashrrev_i32_e32 v13, 31, v12
	v_mov_b32_e32 v22, 0
	s_cbranch_vccnz .LBB0_810
	v_cndmask_b32_e64 v1, 0, 1, s[36:37]
	v_cmp_ne_u32_e64 s[40:41], 1, v1
	s_andn2_b64 vcc, exec, s[36:37]
	s_cbranch_vccz .LBB0_811

; __device__ __forceinline__ void ld8bf(const bf16_t* p, float (&o)[8]) { unpack8(*(const u32x4*)p, o); }
; __device__ __forceinline__ void hg_lf_key(float fp, float lb, float& lf, float& key) {
;     const float e = __expf(-fabsf(fp));
;     const float rc = __builtin_amdgcn_rcpf(1.0f + e);
;     const float sp = fp >= 0.f ? rc : e * rc;
;     const float sn = fp >= 0.f ? e * rc : rc;
;     const float lsig = (fp >= 0.f ? 0.f : fp) + __logf(rc);
;     lf = (lb == 0.f) ? lsig : __logf(lb + (1.0f - lb) * sp); key = (1.0f - lb) * sn;
; __device__ __forceinline__ void w_hg_scan(const float (&lbv)[8], const bf16_t* fsrc, int lane, float (&bb)[4][8], float (&r31)[8], float (&r63)[8]) {
;     ...
;     for (int tb = 0; tb < 4; ++tb) { float fp[8]; ld8bf(fsrc + (size_t)(16 * tb + lo) * NIN, fp);
; #pragma unroll
;         for (int j = 0; j < 8; ++j) { float key; hg_lf_key(fp[j], lbv[j], bb[tb][j], key); } }
.LBB0_541:
	s_ashr_i32 s21, s90, 31
	s_ashr_i32 s27, s90, 4
	s_lshr_b32 s21, s21, 25
	s_add_i32 s35, s27, s21
	s_ashr_i32 s21, s35, 7
	s_and_b32 s35, s35, 0xffffff80
	s_sub_i32 s27, s27, s35
	s_lshl_b32 s35, s21, 13
	s_lshl_b32 s38, s27, 6
	s_add_i32 s35, s38, s35
	s_mul_hi_i32 s38, s35, 0x1800
	s_mulk_i32 s35, 0x1800
	s_add_u32 s91, s8, s35
	s_addc_u32 s92, s9, s38
	s_lshl_b32 s93, s34, 1
	v_and_b32_e32 v34, 15, v33
	s_add_u32 s34, s91, s93
	s_addc_u32 s35, s92, 0
	v_ashrrev_i32_e32 v1, 31, v0
	v_mul_u32_u24_e32 v2, 0xc00, v34
	v_lshl_add_u64 v[4:5], v[0:1], 1, s[34:35]
	v_lshlrev_b32_e32 v2, 1, v2
	v_lshl_add_u64 v[8:9], v[4:5], 0, v[2:3]
	v_add_co_u32_e32 v4, vcc, s73, v8
	v_cmp_neq_f32_e64 s[38:39], 0, v22
	s_nop 0
	v_addc_co_u32_e32 v5, vcc, 0, v9, vcc
	s_waitcnt vmcnt(0) lgkmcnt(0)
	v_mov_b64_e32 v[4:5], v[222:223]
	v_mov_b64_e32 v[6:7], v[224:225]
	v_lshlrev_b32_e32 v14, 16, v4
	v_mul_f32_e64 v2, |v14|, s26
	v_exp_f32_e32 v16, v2
	v_cmp_le_f32_e32 vcc, 0, v14
	v_add_f32_e32 v2, 1.0, v16
	v_rcp_f32_e32 v15, v2
	v_sub_f32_e32 v2, 1.0, v22
	s_and_saveexec_b64 s[34:35], s[38:39]
	s_xor_b64 s[34:35], exec, s[34:35]
	s_cbranch_execz .LBB0_543
	v_mul_f32_e32 v14, v16, v15
	v_cndmask_b32_e32 v14, v14, v15, vcc
	v_fma_f32 v14, v2, v14, v22
	v_cmp_gt_f32_e64 s[42:43], s29, v14
	s_nop 1
	v_cndmask_b32_e64 v15, 0, 32, s[42:43]
	v_ldexp_f32 v14, v14, v15
	v_log_f32_e32 v14, v14
	s_nop 0
	v_mul_f32_e32 v15, 0x3f317217, v14
	v_fma_f32 v15, v14, s17, -v15
	v_fmac_f32_e32 v15, 0x3377d1cf, v14
	v_fmac_f32_e32 v15, 0x3f317217, v14
	v_cmp_lt_f32_e64 s[44:45], |v14|, s22
	s_nop 1
	v_cndmask_b32_e64 v14, v14, v15, s[44:45]
	v_cndmask_b32_e64 v15, 0, v203, s[42:43]
	v_sub_f32_e32 v24, v14, v15

; __device__ __forceinline__ void ld8bf(const bf16_t* p, float (&o)[8]) { unpack8(*(const u32x4*)p, o); }
; __device__ __forceinline__ void hg_lf_key(float fp, float lb, float& lf, float& key) {
;     const float e = __expf(-fabsf(fp));
;     const float rc = __builtin_amdgcn_rcpf(1.0f + e);
;     const float sp = fp >= 0.f ? rc : e * rc;
;     const float sn = fp >= 0.f ? e * rc : rc;
;     const float lsig = (fp >= 0.f ? 0.f : fp) + __logf(rc);
;     lf = (lb == 0.f) ? lsig : __logf(lb + (1.0f - lb) * sp); key = (1.0f - lb) * sn;
; __device__ __forceinline__ void w_hg_scan(const float (&lbv)[8], const bf16_t* fsrc, int lane, float (&bb)[4][8], float (&r31)[8], float (&r63)[8]) {
;     ...
;     for (int tb = 0; tb < 4; ++tb) { float fp[8]; ld8bf(fsrc + (size_t)(16 * tb + lo) * NIN, fp);
; #pragma unroll
;         for (int j = 0; j < 8; ++j) { float key; hg_lf_key(fp[j], lbv[j], bb[tb][j], key); } }
.LBB0_573:
	s_or_b64 exec, exec, s[34:35]
	s_mov_b64 s[34:35], 0x1200
	v_lshl_add_u64 v[14:15], v[8:9], 0, s[34:35]
	v_add_co_u32_e32 v4, vcc, 0x18000, v14
	s_nop 1
	v_addc_co_u32_e32 v5, vcc, 0, v15, vcc
	v_mov_b64_e32 v[4:5], v[226:227]
	v_mov_b64_e32 v[6:7], v[228:229]
	s_waitcnt vmcnt(0) lgkmcnt(0)
	v_lshlrev_b32_e32 v8, 16, v4
	v_mul_f32_e64 v9, |v8|, s26
	v_exp_f32_e32 v41, v9
	v_cmp_le_f32_e32 vcc, 0, v8
	v_add_f32_e32 v9, 1.0, v41
	v_rcp_f32_e32 v9, v9
	s_and_saveexec_b64 s[34:35], s[38:39]
	s_xor_b64 s[34:35], exec, s[34:35]
	s_cbranch_execz .LBB0_575
	v_mul_f32_e32 v8, v41, v9
	v_cndmask_b32_e32 v8, v8, v9, vcc
	v_fma_f32 v8, v2, v8, v22
	v_cmp_gt_f32_e64 s[56:57], s29, v8
	s_nop 1
	v_cndmask_b32_e64 v9, 0, 32, s[56:57]
	v_ldexp_f32 v8, v8, v9
	v_log_f32_e32 v8, v8
	s_nop 0
	v_mul_f32_e32 v9, 0x3f317217, v8
	v_fma_f32 v9, v8, s17, -v9
	v_fmac_f32_e32 v9, 0x3377d1cf, v8
	v_fmac_f32_e32 v9, 0x3f317217, v8
	v_cmp_lt_f32_e64 s[58:59], |v8|, s22
	s_nop 1
	v_cndmask_b32_e64 v8, v8, v9, s[58:59]
	v_cndmask_b32_e64 v9, 0, v203, s[56:57]
	v_sub_f32_e32 v36, v8, v9

; __device__ __forceinline__ void ld8bf(const bf16_t* p, float (&o)[8]) { unpack8(*(const u32x4*)p, o); }
; __device__ __forceinline__ void hg_lf_key(float fp, float lb, float& lf, float& key) {
;     const float e = __expf(-fabsf(fp));
;     const float rc = __builtin_amdgcn_rcpf(1.0f + e);
;     const float sp = fp >= 0.f ? rc : e * rc;
;     const float sn = fp >= 0.f ? e * rc : rc;
;     const float lsig = (fp >= 0.f ? 0.f : fp) + __logf(rc);
;     lf = (lb == 0.f) ? lsig : __logf(lb + (1.0f - lb) * sp); key = (1.0f - lb) * sn;
; __device__ __forceinline__ void w_hg_scan(const float (&lbv)[8], const bf16_t* fsrc, int lane, float (&bb)[4][8], float (&r31)[8], float (&r63)[8]) {
;     ...
;     for (int tb = 0; tb < 4; ++tb) { float fp[8]; ld8bf(fsrc + (size_t)(16 * tb + lo) * NIN, fp);
; #pragma unroll
;         for (int j = 0; j < 8; ++j) { float key; hg_lf_key(fp[j], lbv[j], bb[tb][j], key); } }
.LBB0_605:
	s_or_b64 exec, exec, s[34:35]
	v_add_co_u32_e32 v4, vcc, 0x30000, v14
	s_nop 1
	v_addc_co_u32_e32 v5, vcc, 0, v15, vcc
	v_mov_b64_e32 v[4:5], v[230:231]
	v_mov_b64_e32 v[6:7], v[232:233]
	s_waitcnt vmcnt(0) lgkmcnt(0)
	v_lshlrev_b32_e32 v8, 16, v4
	v_mul_f32_e64 v9, |v8|, s26
	v_exp_f32_e32 v49, v9
	v_cmp_le_f32_e32 vcc, 0, v8
	v_add_f32_e32 v9, 1.0, v49
	v_rcp_f32_e32 v9, v9
	s_and_saveexec_b64 s[34:35], s[38:39]
	s_xor_b64 s[34:35], exec, s[34:35]
	s_cbranch_execz .LBB0_607
	v_mul_f32_e32 v8, v49, v9
	v_cndmask_b32_e32 v8, v8, v9, vcc
	v_fma_f32 v8, v2, v8, v22
	v_cmp_gt_f32_e64 s[56:57], s29, v8
	s_nop 1
	v_cndmask_b32_e64 v9, 0, 32, s[56:57]
	v_ldexp_f32 v8, v8, v9
	v_log_f32_e32 v8, v8
	s_nop 0
	v_mul_f32_e32 v9, 0x3f317217, v8
	v_fma_f32 v9, v8, s17, -v9
	v_fmac_f32_e32 v9, 0x3377d1cf, v8
	v_fmac_f32_e32 v9, 0x3f317217, v8
	v_cmp_lt_f32_e64 s[58:59], |v8|, s22
	s_nop 1
	v_cndmask_b32_e64 v8, v8, v9, s[58:59]
	v_cndmask_b32_e64 v9, 0, v203, s[56:57]
	v_sub_f32_e32 v48, v8, v9

; __device__ __forceinline__ void ld8bf(const bf16_t* p, float (&o)[8]) { unpack8(*(const u32x4*)p, o); }
; __device__ __forceinline__ void hg_lf_key(float fp, float lb, float& lf, float& key) {
;     const float e = __expf(-fabsf(fp));
;     const float rc = __builtin_amdgcn_rcpf(1.0f + e);
;     const float sp = fp >= 0.f ? rc : e * rc;
;     const float sn = fp >= 0.f ? e * rc : rc;
;     const float lsig = (fp >= 0.f ? 0.f : fp) + __logf(rc);
;     lf = (lb == 0.f) ? lsig : __logf(lb + (1.0f - lb) * sp); key = (1.0f - lb) * sn;
; __device__ __forceinline__ void w_hg_scan(const float (&lbv)[8], const bf16_t* fsrc, int lane, float (&bb)[4][8], float (&r31)[8], float (&r63)[8]) {
;     ...
;     for (int tb = 0; tb < 4; ++tb) { float fp[8]; ld8bf(fsrc + (size_t)(16 * tb + lo) * NIN, fp);
; #pragma unroll
;         for (int j = 0; j < 8; ++j) { float key; hg_lf_key(fp[j], lbv[j], bb[tb][j], key); } }
.LBB0_637:
	s_or_b64 exec, exec, s[34:35]
	v_add_co_u32_e32 v4, vcc, 0x48000, v14
	s_nop 1
	v_addc_co_u32_e32 v5, vcc, 0, v15, vcc
	v_mov_b64_e32 v[4:5], v[234:235]
	v_mov_b64_e32 v[6:7], v[236:237]
	s_waitcnt vmcnt(0) lgkmcnt(0)
	v_lshlrev_b32_e32 v8, 16, v4
	v_mul_f32_e64 v9, |v8|, s26
	v_exp_f32_e32 v53, v9
	v_cmp_le_f32_e32 vcc, 0, v8
	v_add_f32_e32 v9, 1.0, v53
	v_rcp_f32_e32 v9, v9
	s_and_saveexec_b64 s[34:35], s[38:39]
	s_xor_b64 s[34:35], exec, s[34:35]
	s_cbranch_execz .LBB0_639
	v_mul_f32_e32 v8, v53, v9
	v_cndmask_b32_e32 v8, v8, v9, vcc
	v_fma_f32 v2, v2, v8, v22
	v_cmp_gt_f32_e64 s[38:39], s29, v2
	s_nop 1
	v_cndmask_b32_e64 v8, 0, 32, s[38:39]
	v_ldexp_f32 v2, v2, v8
	v_log_f32_e32 v2, v2
	s_nop 0
	v_mul_f32_e32 v8, 0x3f317217, v2
	v_fma_f32 v8, v2, s17, -v8
	v_fmac_f32_e32 v8, 0x3377d1cf, v2
	v_fmac_f32_e32 v8, 0x3f317217, v2
	v_cmp_lt_f32_e64 s[56:57], |v2|, s22
	s_nop 1
	v_cndmask_b32_e64 v2, v2, v8, s[56:57]
	v_cndmask_b32_e64 v8, 0, v203, s[38:39]
	v_sub_f32_e32 v69, v2, v8

; __device__ __forceinline__ float bperm_f(int src_lane, float v) { return __builtin_bit_cast(float, __builtin_amdgcn_ds_bpermute(src_lane << 2, __builtin_bit_cast(int, v))); }
; __device__ __forceinline__ float row_sum_incl(float v) { v += dpp_shr0<1>(v); v += dpp_shr0<2>(v); v += dpp_shr0<4>(v); v += dpp_shr0<8>(v); return v; }
; __device__ __forceinline__ float bcast15(float v, int lane) { return bperm_f((lane & 48) | 15, v); }
; __device__ __forceinline__ void w_hg_scan(const float (&lbv)[8], const bf16_t* fsrc, int lane, float (&bb)[4][8], float (&r31)[8], float (&r63)[8]) {
;     ...
;     for (int tb = 0; tb < 4; ++tb) {
; #pragma unroll
;         for (int j = 0; j < 8; ++j) { const float v = row_sum_incl(bb[tb][j]) + carry[j]; bb[tb][j] = v; carry[j] = bcast15(v, lane); if (tb == 1) r31[j] = carry[j]; if (tb == 3) r63[j] = carry[j]; }
;         __builtin_amdgcn_sched_barrier(0);
;     }
; }
.LBB0_669:
	s_or_b64 exec, exec, s[34:35]
	v_add_f32_dpp v28, v28, v28 row_shr:1 row_mask:0xf bank_mask:0xf bound_ctrl:1
	s_lshl_b32 s21, s21, 9
	s_lshl_b32 s27, s27, 2
	v_add_f32_dpp v28, v28, v28 row_shr:2 row_mask:0xf bank_mask:0xf bound_ctrl:1
	s_add_i32 s21, s27, s21
	s_add_i32 s62, s21, s20
	v_add_f32_dpp v28, v28, v28 row_shr:4 row_mask:0xf bank_mask:0xf bound_ctrl:1
	s_ashr_i32 s63, s62, 31
	s_lshl_b64 s[20:21], s[62:63], 8
	v_add_f32_dpp v28, v28, v28 row_shr:8 row_mask:0xf bank_mask:0xf bound_ctrl:1
	v_add_f32_e32 v74, 0, v28
	s_add_u32 s20, s14, s20
	v_add_f32_dpp v28, v29, v29 row_shr:1 row_mask:0xf bank_mask:0xf bound_ctrl:1
	s_addc_u32 s21, s15, s21
	v_lshl_add_u64 v[8:9], v[0:1], 2, s[20:21]
	v_add_f32_dpp v28, v28, v28 row_shr:2 row_mask:0xf bank_mask:0xf bound_ctrl:1
	v_add_f32_dpp v1, v24, v24 row_shr:1 row_mask:0xf bank_mask:0xf bound_ctrl:1
	v_add_f32_dpp v25, v25, v25 row_shr:1 row_mask:0xf bank_mask:0xf bound_ctrl:1
	v_add_f32_dpp v28, v28, v28 row_shr:4 row_mask:0xf bank_mask:0xf bound_ctrl:1
	v_add_f32_dpp v29, v35, v35 row_shr:1 row_mask:0xf bank_mask:0xf bound_ctrl:1
	v_add_f32_dpp v1, v1, v1 row_shr:2 row_mask:0xf bank_mask:0xf bound_ctrl:1
	v_add_f32_dpp v28, v28, v28 row_shr:8 row_mask:0xf bank_mask:0xf bound_ctrl:1
	v_add_f32_e32 v75, 0, v28
	v_add_f32_dpp v25, v25, v25 row_shr:2 row_mask:0xf bank_mask:0xf bound_ctrl:1
	v_add_f32_dpp v28, v31, v31 row_shr:1 row_mask:0xf bank_mask:0xf bound_ctrl:1
	v_add_f32_dpp v29, v29, v29 row_shr:2 row_mask:0xf bank_mask:0xf bound_ctrl:1
	v_add_f32_dpp v1, v1, v1 row_shr:4 row_mask:0xf bank_mask:0xf bound_ctrl:1
	v_add_f32_dpp v28, v28, v28 row_shr:2 row_mask:0xf bank_mask:0xf bound_ctrl:1
	v_add_f32_dpp v25, v25, v25 row_shr:4 row_mask:0xf bank_mask:0xf bound_ctrl:1
	v_add_f32_dpp v29, v29, v29 row_shr:4 row_mask:0xf bank_mask:0xf bound_ctrl:1
	v_add_f32_dpp v28, v28, v28 row_shr:4 row_mask:0xf bank_mask:0xf bound_ctrl:1
	v_lshlrev_b32_e32 v2, 2, v33
	v_add_f32_dpp v1, v1, v1 row_shr:8 row_mask:0xf bank_mask:0xf bound_ctrl:1
	v_add_f32_dpp v25, v25, v25 row_shr:8 row_mask:0xf bank_mask:0xf bound_ctrl:1
	v_add_f32_dpp v28, v28, v28 row_shr:8 row_mask:0xf bank_mask:0xf bound_ctrl:1
	v_add_f32_dpp v29, v29, v29 row_shr:8 row_mask:0xf bank_mask:0xf bound_ctrl:1
	v_and_b32_e32 v30, 0xc0, v2
	v_add_f32_e32 v24, 0, v1
	v_add_f32_e32 v25, 0, v25
	v_add_f32_e32 v28, 0, v28
	v_add_f32_e32 v29, 0, v29
	ds_bpermute_b32 v1, v30, v24 offset:60
	ds_bpermute_b32 v38, v30, v25 offset:60
	v_add_f32_dpp v26, v26, v26 row_shr:1 row_mask:0xf bank_mask:0xf bound_ctrl:1
	v_add_f32_dpp v27, v27, v27 row_shr:1 row_mask:0xf bank_mask:0xf bound_ctrl:1
	ds_bpermute_b32 v40, v30, v74 offset:60
	ds_bpermute_b32 v31, v30, v28 offset:60
	ds_bpermute_b32 v35, v30, v29 offset:60
	v_add_f32_dpp v26, v26, v26 row_shr:2 row_mask:0xf bank_mask:0xf bound_ctrl:1
	v_add_f32_dpp v27, v27, v27 row_shr:2 row_mask:0xf bank_mask:0xf bound_ctrl:1
	s_mov_b64 s[34:35], 0x18000
	v_add_f32_dpp v26, v26, v26 row_shr:4 row_mask:0xf bank_mask:0xf bound_ctrl:1
	v_add_f32_dpp v27, v27, v27 row_shr:4 row_mask:0xf bank_mask:0xf bound_ctrl:1
	v_lshl_add_u64 v[10:11], v[14:15], 0, s[34:35]
	v_add_f32_dpp v26, v26, v26 row_shr:8 row_mask:0xf bank_mask:0xf bound_ctrl:1
	v_add_f32_dpp v27, v27, v27 row_shr:8 row_mask:0xf bank_mask:0xf bound_ctrl:1
	v_lshl_add_u32 v2, v0, 1, s6
	v_cmp_eq_u32_e64 s[38:39], 0, v34
	v_add_f32_e32 v72, 0, v26
	v_add_f32_e32 v73, 0, v27
	ds_bpermute_b32 v26, v30, v72 offset:60
	ds_bpermute_b32 v27, v30, v73 offset:60
	ds_bpermute_b32 v53, v30, v75 offset:60
	v_add_f32_dpp v36, v36, v36 row_shr:1 row_mask:0xf bank_mask:0xf bound_ctrl:1
	s_nop 1
	v_add_f32_dpp v36, v36, v36 row_shr:2 row_mask:0xf bank_mask:0xf bound_ctrl:1
	s_nop 1
	v_add_f32_dpp v36, v36, v36 row_shr:4 row_mask:0xf bank_mask:0xf bound_ctrl:1
	s_nop 1
	v_add_f32_dpp v36, v36, v36 row_shr:8 row_mask:0xf bank_mask:0xf bound_ctrl:1
	s_waitcnt lgkmcnt(7)
	v_add_f32_e32 v68, v36, v1
	ds_bpermute_b32 v1, v30, v68 offset:60
	v_add_f32_dpp v36, v41, v41 row_shr:1 row_mask:0xf bank_mask:0xf bound_ctrl:1
	v_add_f32_dpp v41, v46, v46 row_shr:1 row_mask:0xf bank_mask:0xf bound_ctrl:1
	s_nop 0
	v_add_f32_dpp v36, v36, v36 row_shr:2 row_mask:0xf bank_mask:0xf bound_ctrl:1
	v_add_f32_dpp v41, v41, v41 row_shr:2 row_mask:0xf bank_mask:0xf bound_ctrl:1
	s_nop 0
	v_add_f32_dpp v36, v36, v36 row_shr:4 row_mask:0xf bank_mask:0xf bound_ctrl:1
	v_add_f32_dpp v41, v41, v41 row_shr:4 row_mask:0xf bank_mask:0xf bound_ctrl:1
	s_nop 0
	v_add_f32_dpp v36, v36, v36 row_shr:8 row_mask:0xf bank_mask:0xf bound_ctrl:1
	s_waitcnt lgkmcnt(7)
	v_add_f32_e32 v67, v36, v38
	v_add_f32_dpp v38, v42, v42 row_shr:1 row_mask:0xf bank_mask:0xf bound_ctrl:1
	v_add_f32_dpp v41, v41, v41 row_shr:8 row_mask:0xf bank_mask:0xf bound_ctrl:1
	s_waitcnt lgkmcnt(5)
	v_add_f32_e32 v59, v41, v31
	v_add_f32_dpp v38, v38, v38 row_shr:2 row_mask:0xf bank_mask:0xf bound_ctrl:1
	v_add_f32_dpp v41, v47, v47 row_shr:1 row_mask:0xf bank_mask:0xf bound_ctrl:1
	ds_bpermute_b32 v36, v30, v67 offset:60
	v_add_f32_dpp v38, v38, v38 row_shr:4 row_mask:0xf bank_mask:0xf bound_ctrl:1
	v_add_f32_dpp v41, v41, v41 row_shr:2 row_mask:0xf bank_mask:0xf bound_ctrl:1
	ds_bpermute_b32 v31, v30, v59 offset:60
	v_add_f32_dpp v38, v38, v38 row_shr:8 row_mask:0xf bank_mask:0xf bound_ctrl:1
	s_waitcnt lgkmcnt(5)
; __device__ __forceinline__ float bperm_f(int src_lane, float v) { return __builtin_bit_cast(float, __builtin_amdgcn_ds_bpermute(src_lane << 2, __builtin_bit_cast(int, v))); }
; __device__ __forceinline__ float row_sum_incl(float v) { v += dpp_shr0<1>(v); v += dpp_shr0<2>(v); v += dpp_shr0<4>(v); v += dpp_shr0<8>(v); return v; }
; __device__ __forceinline__ float bcast15(float v, int lane) { return bperm_f((lane & 48) | 15, v); }
; __device__ __forceinline__ void w_hg_scan(const float (&lbv)[8], const bf16_t* fsrc, int lane, float (&bb)[4][8], float (&r31)[8], float (&r63)[8]) {
;     ...
;     for (int tb = 0; tb < 4; ++tb) {
; #pragma unroll
;         for (int j = 0; j < 8; ++j) { const float v = row_sum_incl(bb[tb][j]) + carry[j]; bb[tb][j] = v; carry[j] = bcast15(v, lane); if (tb == 1) r31[j] = carry[j]; if (tb == 3) r63[j] = carry[j]; }
;         __builtin_amdgcn_sched_barrier(0);
;     }
; }
	v_add_f32_e32 v65, v38, v26
	v_add_f32_dpp v41, v41, v41 row_shr:4 row_mask:0xf bank_mask:0xf bound_ctrl:1
	v_add_f32_dpp v38, v43, v43 row_shr:1 row_mask:0xf bank_mask:0xf bound_ctrl:1
	ds_bpermute_b32 v26, v30, v65 offset:60
	v_add_f32_dpp v41, v41, v41 row_shr:8 row_mask:0xf bank_mask:0xf bound_ctrl:1
	v_add_f32_dpp v38, v38, v38 row_shr:2 row_mask:0xf bank_mask:0xf bound_ctrl:1
	v_add_f32_e32 v58, v41, v35
	ds_bpermute_b32 v35, v30, v58 offset:60
	v_add_f32_dpp v38, v38, v38 row_shr:4 row_mask:0xf bank_mask:0xf bound_ctrl:1
	s_nop 1
	v_add_f32_dpp v38, v38, v38 row_shr:8 row_mask:0xf bank_mask:0xf bound_ctrl:1
	s_waitcnt lgkmcnt(6)
	v_add_f32_e32 v64, v38, v27
	ds_bpermute_b32 v27, v30, v64 offset:60
	v_add_f32_dpp v38, v44, v44 row_shr:1 row_mask:0xf bank_mask:0xf bound_ctrl:1
	s_nop 1
	v_add_f32_dpp v38, v38, v38 row_shr:2 row_mask:0xf bank_mask:0xf bound_ctrl:1
	s_nop 1
	v_add_f32_dpp v38, v38, v38 row_shr:4 row_mask:0xf bank_mask:0xf bound_ctrl:1
	s_nop 1
	v_add_f32_dpp v38, v38, v38 row_shr:8 row_mask:0xf bank_mask:0xf bound_ctrl:1
	v_add_f32_e32 v62, v38, v40
	v_add_f32_dpp v40, v45, v45 row_shr:1 row_mask:0xf bank_mask:0xf bound_ctrl:1
	ds_bpermute_b32 v38, v30, v62 offset:60
	s_nop 0
	v_add_f32_dpp v40, v40, v40 row_shr:2 row_mask:0xf bank_mask:0xf bound_ctrl:1
	s_nop 1
	v_add_f32_dpp v40, v40, v40 row_shr:4 row_mask:0xf bank_mask:0xf bound_ctrl:1
	s_nop 1
	v_add_f32_dpp v40, v40, v40 row_shr:8 row_mask:0xf bank_mask:0xf bound_ctrl:1
	s_waitcnt lgkmcnt(7)
	v_add_f32_e32 v61, v40, v53
	ds_bpermute_b32 v40, v30, v61 offset:60
	v_add_f32_dpp v41, v48, v48 row_shr:1 row_mask:0xf bank_mask:0xf bound_ctrl:1
	s_nop 1
	v_add_f32_dpp v41, v41, v41 row_shr:2 row_mask:0xf bank_mask:0xf bound_ctrl:1
	s_nop 1
	v_add_f32_dpp v41, v41, v41 row_shr:4 row_mask:0xf bank_mask:0xf bound_ctrl:1
	s_nop 1
	v_add_f32_dpp v41, v41, v41 row_shr:8 row_mask:0xf bank_mask:0xf bound_ctrl:1
	s_waitcnt lgkmcnt(7)
	v_add_f32_e32 v57, v41, v1
	ds_bpermute_b32 v1, v30, v57 offset:60
	v_add_f32_dpp v41, v49, v49 row_shr:1 row_mask:0xf bank_mask:0xf bound_ctrl:1
	s_nop 1
	v_add_f32_dpp v41, v41, v41 row_shr:2 row_mask:0xf bank_mask:0xf bound_ctrl:1
	s_nop 1
	v_add_f32_dpp v41, v41, v41 row_shr:4 row_mask:0xf bank_mask:0xf bound_ctrl:1
	s_nop 1
	v_add_f32_dpp v41, v41, v41 row_shr:8 row_mask:0xf bank_mask:0xf bound_ctrl:1
	s_waitcnt lgkmcnt(7)
	v_add_f32_e32 v56, v41, v36
	ds_bpermute_b32 v36, v30, v56 offset:60
	v_add_f32_dpp v41, v50, v50 row_shr:1 row_mask:0xf bank_mask:0xf bound_ctrl:1
	s_nop 1
	v_add_f32_dpp v41, v41, v41 row_shr:2 row_mask:0xf bank_mask:0xf bound_ctrl:1
	s_nop 1
	v_add_f32_dpp v41, v41, v41 row_shr:4 row_mask:0xf bank_mask:0xf bound_ctrl:1
	s_nop 1
	v_add_f32_dpp v41, v41, v41 row_shr:8 row_mask:0xf bank_mask:0xf bound_ctrl:1
	s_waitcnt lgkmcnt(6)
	v_add_f32_e32 v55, v41, v26
	ds_bpermute_b32 v26, v30, v55 offset:60
	v_add_f32_dpp v41, v51, v51 row_shr:1 row_mask:0xf bank_mask:0xf bound_ctrl:1
	s_nop 1
	v_add_f32_dpp v41, v41, v41 row_shr:2 row_mask:0xf bank_mask:0xf bound_ctrl:1
	s_nop 1
	v_add_f32_dpp v41, v41, v41 row_shr:4 row_mask:0xf bank_mask:0xf bound_ctrl:1
	s_nop 1
	v_add_f32_dpp v41, v41, v41 row_shr:8 row_mask:0xf bank_mask:0xf bound_ctrl:1
	s_waitcnt lgkmcnt(5)
	v_add_f32_e32 v54, v41, v27
	ds_bpermute_b32 v27, v30, v54 offset:60
	v_add_f32_dpp v41, v52, v52 row_shr:1 row_mask:0xf bank_mask:0xf bound_ctrl:1
	s_nop 1
	v_add_f32_dpp v41, v41, v41 row_shr:2 row_mask:0xf bank_mask:0xf bound_ctrl:1
	s_nop 1
	v_add_f32_dpp v41, v41, v41 row_shr:4 row_mask:0xf bank_mask:0xf bound_ctrl:1
	s_nop 1
	v_add_f32_dpp v41, v41, v41 row_shr:8 row_mask:0xf bank_mask:0xf bound_ctrl:1
	s_waitcnt lgkmcnt(5)
	v_add_f32_e32 v53, v41, v38
	v_add_f32_dpp v38, v60, v60 row_shr:1 row_mask:0xf bank_mask:0xf bound_ctrl:1
	ds_bpermute_b32 v41, v30, v53 offset:60
	s_nop 0
	v_add_f32_dpp v38, v38, v38 row_shr:2 row_mask:0xf bank_mask:0xf bound_ctrl:1
	s_nop 1
	v_add_f32_dpp v38, v38, v38 row_shr:4 row_mask:0xf bank_mask:0xf bound_ctrl:1
	s_nop 1
	v_add_f32_dpp v38, v38, v38 row_shr:8 row_mask:0xf bank_mask:0xf bound_ctrl:1
	s_waitcnt lgkmcnt(5)
	v_add_f32_e32 v52, v38, v40
	ds_bpermute_b32 v40, v30, v52 offset:60
	v_add_f32_dpp v38, v63, v63 row_shr:1 row_mask:0xf bank_mask:0xf bound_ctrl:1
	s_nop 1
	v_add_f32_dpp v38, v38, v38 row_shr:2 row_mask:0xf bank_mask:0xf bound_ctrl:1
	s_nop 1
	v_add_f32_dpp v38, v38, v38 row_shr:4 row_mask:0xf bank_mask:0xf bound_ctrl:1
	s_nop 1
	v_add_f32_dpp v38, v38, v38 row_shr:8 row_mask:0xf bank_mask:0xf bound_ctrl:1
	v_add_f32_e32 v51, v38, v31
	v_add_f32_dpp v31, v66, v66 row_shr:1 row_mask:0xf bank_mask:0xf bound_ctrl:1
	ds_bpermute_b32 v42, v30, v51 offset:60
	s_nop 0
	v_add_f32_dpp v31, v31, v31 row_shr:2 row_mask:0xf bank_mask:0xf bound_ctrl:1
	s_nop 1
	v_add_f32_dpp v31, v31, v31 row_shr:4 row_mask:0xf bank_mask:0xf bound_ctrl:1
	s_nop 1
	v_add_f32_dpp v31, v31, v31 row_shr:8 row_mask:0xf bank_mask:0xf bound_ctrl:1
	v_add_f32_e32 v50, v31, v35
	ds_bpermute_b32 v49, v30, v50 offset:60
	v_add_f32_dpp v4, v4, v4 row_shr:1 row_mask:0xf bank_mask:0xf bound_ctrl:1
	v_add_f32_dpp v31, v69, v69 row_shr:1 row_mask:0xf bank_mask:0xf bound_ctrl:1
	s_nop 0
	v_add_f32_dpp v4, v4, v4 row_shr:2 row_mask:0xf bank_mask:0xf bound_ctrl:1
	v_add_f32_dpp v31, v31, v31 row_shr:2 row_mask:0xf bank_mask:0xf bound_ctrl:1
	s_nop 0
	v_add_f32_dpp v4, v4, v4 row_shr:4 row_mask:0xf bank_mask:0xf bound_ctrl:1
	v_add_f32_dpp v31, v31, v31 row_shr:4 row_mask:0xf bank_mask:0xf bound_ctrl:1
	s_nop 0
	v_add_f32_dpp v4, v4, v4 row_shr:8 row_mask:0xf bank_mask:0xf bound_ctrl:1
	s_waitcnt lgkmcnt(6)
; #define LAS __attribute__((address_space(3)))
; __device__ __forceinline__ u32x4 pack8(const float (&v)[8]) { u32x4 w; w.x = pk2(v[0], v[1]); w.y = pk2(v[2], v[3]); w.z = pk2(v[4], v[5]); w.w = pk2(v[6], v[7]); return w; }
; __device__ __forceinline__ void ld8bf(const bf16_t* p, float (&o)[8]) { unpack8(*(const u32x4*)p, o); }
; __device__ __forceinline__ void hg_lf_key(float fp, float lb, float& lf, float& key) {
;     const float e = __expf(-fabsf(fp));
;     const float rc = __builtin_amdgcn_rcpf(1.0f + e);
;     const float sp = fp >= 0.f ? rc : e * rc;
;     const float sn = fp >= 0.f ? e * rc : rc;
;     const float lsig = (fp >= 0.f ? 0.f : fp) + __logf(rc);
;     lf = (lb == 0.f) ? lsig : __logf(lb + (1.0f - lb) * sp); key = (1.0f - lb) * sn;
; }
; __device__ __forceinline__ void w_hg_m1(const Args& a, int l, unsigned char* ws, const bf16_t* proj, LAS unsigned char* wl, int b, int ck_, int h, int lane) {
;     ...
;         for (int tb = 0; tb < 4; ++tb) { float fp[8]; ld8bf(fsrc + (size_t)(16 * tb + lo) * NIN, fp);
;             float kb[8];
; #pragma unroll
;             for (int j = 0; j < 8; ++j) { float lf, key; hg_lf_key(fp[j], lbv[j], lf, key); kb[j] = key * __expf(r63[j] - bb[tb][j]); }
;             *(LAS u32x4*)(kT + (16 * tb + lo) * LD + 32 * kk + 8 * fq) = pack8(kb); }
;         if (lo == 0) { float* dp = (float*)(ws + WS_HGDEC) + (size_t)((b * NCH + ck_) * 4 + h) * 64 + 32 * kk + 8 * fq;
; #pragma unroll
;             for (int j = 0; j < 8; ++j) dp[j] = __expf(r63[j]); }
	v_add_f32_e32 v47, v4, v36
	v_add_f32_dpp v31, v31, v31 row_shr:8 row_mask:0xf bank_mask:0xf bound_ctrl:1
	v_add_f32_dpp v4, v70, v70 row_shr:1 row_mask:0xf bank_mask:0xf bound_ctrl:1
	v_add_f32_e32 v48, v31, v1
	ds_bpermute_b32 v1, v30, v48 offset:60
	v_add_f32_dpp v4, v4, v4 row_shr:2 row_mask:0xf bank_mask:0xf bound_ctrl:1
	ds_bpermute_b32 v31, v30, v47 offset:60
	s_nop 0
	v_add_f32_dpp v4, v4, v4 row_shr:4 row_mask:0xf bank_mask:0xf bound_ctrl:1
	s_nop 1
	v_add_f32_dpp v4, v4, v4 row_shr:8 row_mask:0xf bank_mask:0xf bound_ctrl:1
	s_waitcnt lgkmcnt(7)
	v_add_f32_e32 v46, v4, v26
	ds_bpermute_b32 v36, v30, v46 offset:60
	v_add_f32_dpp v4, v5, v5 row_shr:1 row_mask:0xf bank_mask:0xf bound_ctrl:1
	s_nop 1
	v_add_f32_dpp v4, v4, v4 row_shr:2 row_mask:0xf bank_mask:0xf bound_ctrl:1
	s_nop 1
	v_add_f32_dpp v4, v4, v4 row_shr:4 row_mask:0xf bank_mask:0xf bound_ctrl:1
	s_nop 1
	v_add_f32_dpp v4, v4, v4 row_shr:8 row_mask:0xf bank_mask:0xf bound_ctrl:1
	s_waitcnt lgkmcnt(7)
	v_add_f32_e32 v45, v4, v27
	ds_bpermute_b32 v38, v30, v45 offset:60
	v_add_f32_dpp v4, v37, v37 row_shr:1 row_mask:0xf bank_mask:0xf bound_ctrl:1
	s_nop 1
	v_add_f32_dpp v4, v4, v4 row_shr:2 row_mask:0xf bank_mask:0xf bound_ctrl:1
	s_nop 1
	v_add_f32_dpp v4, v4, v4 row_shr:4 row_mask:0xf bank_mask:0xf bound_ctrl:1
	s_nop 1
	v_add_f32_dpp v4, v4, v4 row_shr:8 row_mask:0xf bank_mask:0xf bound_ctrl:1
	s_waitcnt lgkmcnt(7)
	v_add_f32_e32 v44, v4, v41
	ds_bpermute_b32 v35, v30, v44 offset:60
	v_add_f32_dpp v4, v6, v6 row_shr:1 row_mask:0xf bank_mask:0xf bound_ctrl:1
	s_nop 1
	v_add_f32_dpp v4, v4, v4 row_shr:2 row_mask:0xf bank_mask:0xf bound_ctrl:1
	s_nop 1
	v_add_f32_dpp v4, v4, v4 row_shr:4 row_mask:0xf bank_mask:0xf bound_ctrl:1
	s_nop 1
	v_add_f32_dpp v4, v4, v4 row_shr:8 row_mask:0xf bank_mask:0xf bound_ctrl:1
	s_waitcnt lgkmcnt(7)
	v_add_f32_e32 v43, v4, v40
	ds_bpermute_b32 v37, v30, v43 offset:60
	v_add_f32_dpp v4, v39, v39 row_shr:1 row_mask:0xf bank_mask:0xf bound_ctrl:1
	s_nop 1
	v_add_f32_dpp v4, v4, v4 row_shr:2 row_mask:0xf bank_mask:0xf bound_ctrl:1
	s_nop 1
	v_add_f32_dpp v4, v4, v4 row_shr:4 row_mask:0xf bank_mask:0xf bound_ctrl:1
	s_nop 1
	v_add_f32_dpp v4, v4, v4 row_shr:8 row_mask:0xf bank_mask:0xf bound_ctrl:1
	s_waitcnt lgkmcnt(7)
	v_add_f32_e32 v42, v4, v42
	ds_bpermute_b32 v39, v30, v42 offset:60
	v_add_f32_dpp v4, v7, v7 row_shr:1 row_mask:0xf bank_mask:0xf bound_ctrl:1
	s_nop 1
	v_add_f32_dpp v4, v4, v4 row_shr:2 row_mask:0xf bank_mask:0xf bound_ctrl:1
	s_nop 1
	v_add_f32_dpp v4, v4, v4 row_shr:4 row_mask:0xf bank_mask:0xf bound_ctrl:1
	s_nop 1
	v_add_f32_dpp v4, v4, v4 row_shr:8 row_mask:0xf bank_mask:0xf bound_ctrl:1
	s_waitcnt lgkmcnt(7)
	v_add_f32_e32 v41, v4, v49
	ds_bpermute_b32 v40, v30, v41 offset:60
	v_mov_b64_e32 v[4:5], v[222:223]
	v_mov_b64_e32 v[6:7], v[224:225]
	s_waitcnt lgkmcnt(0)
	v_sub_f32_e32 v24, v1, v24
	v_sub_f32_e32 v25, v31, v25
	v_mul_f32_e32 v24, 0x3fb8aa3b, v24
	v_mul_f32_e32 v25, 0x3fb8aa3b, v25
	v_exp_f32_e32 v24, v24
	v_exp_f32_e32 v25, v25
	v_pk_add_f32 v[22:23], v[22:23], 1.0 op_sel_hi:[1,0] neg_lo:[1,0] neg_hi:[1,0]
	v_pk_add_f32 v[20:21], v[20:21], 1.0 op_sel_hi:[1,0] neg_lo:[1,0] neg_hi:[1,0]
	v_pk_add_f32 v[18:19], v[18:19], 1.0 op_sel_hi:[1,0] neg_lo:[1,0] neg_hi:[1,0]
	s_waitcnt vmcnt(0)
	v_lshlrev_b32_e32 v49, 16, v4
	v_mul_f32_e64 v26, |v49|, s26
	v_exp_f32_e32 v26, v26
	v_and_b32_e32 v4, 0xffff0000, v4
	v_cmp_le_f32_e32 vcc, 0, v49
	v_cmp_le_f32_e64 s[42:43], 0, v4
	v_add_f32_e32 v27, 1.0, v26
	v_rcp_f32_e32 v70, v27
	v_mul_f32_e64 v27, |v4|, s26
	v_exp_f32_e32 v27, v27
	v_sub_f32_e32 v4, v36, v72
	v_mul_f32_e32 v4, 0x3fb8aa3b, v4
	v_lshlrev_b32_e32 v49, 16, v5
	v_add_f32_e32 v60, 1.0, v27
	v_rcp_f32_e32 v71, v60
	v_and_b32_e32 v60, 0xffff0000, v5
	v_pk_mul_f32 v[26:27], v[26:27], v[70:71]
	s_nop 0
	v_cndmask_b32_e64 v27, v71, v27, s[42:43]
	v_cndmask_b32_e32 v26, v70, v26, vcc
	v_pk_mul_f32 v[26:27], v[22:23], v[26:27]
	v_cmp_le_f32_e32 vcc, 0, v49
	v_pk_mul_f32 v[24:25], v[24:25], v[26:27]
	v_exp_f32_e32 v26, v4
	v_sub_f32_e32 v4, v38, v73
	v_mul_f32_e32 v4, 0x3fb8aa3b, v4
	v_exp_f32_e32 v27, v4
	v_mul_f32_e64 v4, |v49|, s26
	v_exp_f32_e32 v4, v4
	v_lshlrev_b32_e32 v49, 16, v6
	v_cmp_le_f32_e64 s[42:43], 0, v60
	v_and_b32_e32 v6, 0xffff0000, v6
	v_add_f32_e32 v5, 1.0, v4
	v_rcp_f32_e32 v70, v5
	v_mul_f32_e64 v5, |v60|, s26
	v_exp_f32_e32 v5, v5
	v_mul_f32_e64 v60, |v49|, s26
	v_cvt_pk_bf16_f32 v24, v24, v25
	v_add_f32_e32 v63, 1.0, v5
	v_rcp_f32_e32 v71, v63
	s_nop 0
	v_pk_mul_f32 v[4:5], v[4:5], v[70:71]
	s_nop 0
	v_cndmask_b32_e32 v4, v70, v4, vcc
	v_exp_f32_e32 v70, v60
	v_cndmask_b32_e64 v5, v71, v5, s[42:43]
	v_cmp_le_f32_e64 s[42:43], 0, v6
	v_pk_mul_f32 v[4:5], v[20:21], v[4:5]
	v_add_f32_e32 v60, 1.0, v70
	v_rcp_f32_e32 v72, v60
	v_mul_f32_e64 v60, |v6|, s26
	v_exp_f32_e32 v71, v60
	v_sub_f32_e32 v6, v39, v28
	v_mul_f32_e32 v6, 0x3fb8aa3b, v6
	v_exp_f32_e32 v28, v6
	v_add_f32_e32 v60, 1.0, v71
	v_sub_f32_e32 v6, v40, v29
	v_rcp_f32_e32 v73, v60
	v_cmp_le_f32_e32 vcc, 0, v49
	v_mul_f32_e32 v6, 0x3fb8aa3b, v6
	v_lshlrev_b32_e32 v49, 16, v7
	v_pk_mul_f32 v[4:5], v[26:27], v[4:5]
	v_sub_f32_e32 v26, v35, v74
	v_sub_f32_e32 v27, v37, v75
	v_exp_f32_e32 v29, v6
	v_mul_f32_e64 v6, |v49|, s26
	v_mul_f32_e32 v26, 0x3fb8aa3b, v26
	v_mul_f32_e32 v27, 0x3fb8aa3b, v27
	v_exp_f32_e32 v6, v6
	v_exp_f32_e32 v26, v26
	v_exp_f32_e32 v27, v27
	v_pk_mul_f32 v[70:71], v[70:71], v[72:73]
	v_and_b32_e32 v60, 0xffff0000, v7
	v_cndmask_b32_e64 v71, v73, v71, s[42:43]
	v_cndmask_b32_e32 v70, v72, v70, vcc
	v_pk_mul_f32 v[70:71], v[18:19], v[70:71]
	v_add_f32_e32 v7, 1.0, v6
	v_pk_mul_f32 v[26:27], v[26:27], v[70:71]
	v_rcp_f32_e32 v70, v7
	v_mul_f32_e64 v7, |v60|, s26
	v_exp_f32_e32 v7, v7
	v_cmp_le_f32_e32 vcc, 0, v49
	v_cmp_le_f32_e64 s[42:43], 0, v60
	v_cvt_pk_bf16_f32 v25, v4, v5
	v_add_f32_e32 v63, 1.0, v7
	v_rcp_f32_e32 v71, v63
	v_cvt_pk_bf16_f32 v26, v26, v27
	v_mad_u32_u24 v49, v34, s23, v2
	v_pk_mul_f32 v[6:7], v[6:7], v[70:71]
	s_nop 0
	v_cndmask_b32_e64 v7, v71, v7, s[42:43]
	v_cndmask_b32_e32 v6, v70, v6, vcc
	v_pk_mul_f32 v[6:7], v[16:17], v[6:7]
	s_nop 0
	v_pk_mul_f32 v[6:7], v[28:29], v[6:7]
	s_nop 0
	v_cvt_pk_bf16_f32 v27, v6, v7
	ds_write_b128 v49, v[24:27] offset:9216
	v_mov_b64_e32 v[4:5], v[226:227]
	v_mov_b64_e32 v[6:7], v[228:229]
	v_sub_f32_e32 v24, v1, v68
	v_sub_f32_e32 v25, v31, v67
	v_mul_f32_e32 v24, 0x3fb8aa3b, v24
	v_mul_f32_e32 v25, 0x3fb8aa3b, v25
	v_exp_f32_e32 v24, v24
	v_exp_f32_e32 v25, v25
	s_waitcnt vmcnt(0) lgkmcnt(0)
; #define LAS __attribute__((address_space(3)))
; __device__ __forceinline__ u32x4 pack8(const float (&v)[8]) { u32x4 w; w.x = pk2(v[0], v[1]); w.y = pk2(v[2], v[3]); w.z = pk2(v[4], v[5]); w.w = pk2(v[6], v[7]); return w; }
; __device__ __forceinline__ void ld8bf(const bf16_t* p, float (&o)[8]) { unpack8(*(const u32x4*)p, o); }
; __device__ __forceinline__ void hg_lf_key(float fp, float lb, float& lf, float& key) {
;     const float e = __expf(-fabsf(fp));
;     const float rc = __builtin_amdgcn_rcpf(1.0f + e);
;     const float sp = fp >= 0.f ? rc : e * rc;
;     const float sn = fp >= 0.f ? e * rc : rc;
;     const float lsig = (fp >= 0.f ? 0.f : fp) + __logf(rc);
;     lf = (lb == 0.f) ? lsig : __logf(lb + (1.0f - lb) * sp); key = (1.0f - lb) * sn;
; }
; __device__ __forceinline__ void w_hg_m1(const Args& a, int l, unsigned char* ws, const bf16_t* proj, LAS unsigned char* wl, int b, int ck_, int h, int lane) {
;     ...
;         for (int tb = 0; tb < 4; ++tb) { float fp[8]; ld8bf(fsrc + (size_t)(16 * tb + lo) * NIN, fp);
;             float kb[8];
; #pragma unroll
;             for (int j = 0; j < 8; ++j) { float lf, key; hg_lf_key(fp[j], lbv[j], lf, key); kb[j] = key * __expf(r63[j] - bb[tb][j]); }
;             *(LAS u32x4*)(kT + (16 * tb + lo) * LD + 32 * kk + 8 * fq) = pack8(kb); }
;         if (lo == 0) { float* dp = (float*)(ws + WS_HGDEC) + (size_t)((b * NCH + ck_) * 4 + h) * 64 + 32 * kk + 8 * fq;
; #pragma unroll
;             for (int j = 0; j < 8; ++j) dp[j] = __expf(r63[j]); }
	v_lshlrev_b32_e32 v60, 16, v4
	v_mul_f32_e64 v26, |v60|, s26
	v_exp_f32_e32 v26, v26
	v_and_b32_e32 v4, 0xffff0000, v4
	v_cmp_le_f32_e32 vcc, 0, v60
	v_cmp_le_f32_e64 s[42:43], 0, v4
	v_add_f32_e32 v27, 1.0, v26
	v_rcp_f32_e32 v28, v27
	v_mul_f32_e64 v27, |v4|, s26
	v_exp_f32_e32 v27, v27
	v_sub_f32_e32 v4, v36, v65
	v_mul_f32_e32 v4, 0x3fb8aa3b, v4
	v_lshlrev_b32_e32 v60, 16, v5
	v_add_f32_e32 v29, 1.0, v27
	v_rcp_f32_e32 v29, v29
	v_and_b32_e32 v63, 0xffff0000, v5
	v_pk_mul_f32 v[26:27], v[26:27], v[28:29]
	s_nop 0
	v_cndmask_b32_e64 v27, v29, v27, s[42:43]
	v_cndmask_b32_e32 v26, v28, v26, vcc
	v_pk_mul_f32 v[26:27], v[22:23], v[26:27]
	v_cmp_le_f32_e32 vcc, 0, v60
	v_pk_mul_f32 v[24:25], v[24:25], v[26:27]
	v_exp_f32_e32 v26, v4
	v_sub_f32_e32 v4, v38, v64
	v_mul_f32_e32 v4, 0x3fb8aa3b, v4
	v_exp_f32_e32 v27, v4
	v_mul_f32_e64 v4, |v60|, s26
	v_exp_f32_e32 v4, v4
	v_cmp_le_f32_e64 s[42:43], 0, v63
	v_cvt_pk_bf16_f32 v24, v24, v25
	v_add_f32_e32 v5, 1.0, v4
	v_rcp_f32_e32 v28, v5
	v_mul_f32_e64 v5, |v63|, s26
	v_exp_f32_e32 v5, v5
	s_nop 0
	v_add_f32_e32 v29, 1.0, v5
	v_rcp_f32_e32 v29, v29
	s_nop 0
	v_pk_mul_f32 v[4:5], v[4:5], v[28:29]
	s_nop 0
	v_cndmask_b32_e64 v5, v29, v5, s[42:43]
	v_cndmask_b32_e32 v4, v28, v4, vcc
	v_pk_mul_f32 v[4:5], v[20:21], v[4:5]
	s_nop 0
	v_pk_mul_f32 v[4:5], v[26:27], v[4:5]
	v_sub_f32_e32 v26, v35, v62
	v_lshlrev_b32_e32 v62, 16, v6
	v_mul_f32_e64 v28, |v62|, s26
	v_exp_f32_e32 v28, v28
	v_and_b32_e32 v6, 0xffff0000, v6
	v_sub_f32_e32 v27, v37, v61
	v_mul_f32_e32 v26, 0x3fb8aa3b, v26
	v_add_f32_e32 v29, 1.0, v28
	v_rcp_f32_e32 v60, v29
	v_mul_f32_e64 v29, |v6|, s26
	v_exp_f32_e32 v29, v29
	v_mul_f32_e32 v27, 0x3fb8aa3b, v27
	v_exp_f32_e32 v26, v26
	v_exp_f32_e32 v27, v27
	v_add_f32_e32 v61, 1.0, v29
	v_rcp_f32_e32 v61, v61
	v_cmp_le_f32_e32 vcc, 0, v62
	v_cmp_le_f32_e64 s[42:43], 0, v6
	v_sub_f32_e32 v6, v39, v59
	v_pk_mul_f32 v[28:29], v[28:29], v[60:61]
	v_mul_f32_e32 v6, 0x3fb8aa3b, v6
	v_cndmask_b32_e64 v29, v61, v29, s[42:43]
	v_cndmask_b32_e32 v28, v60, v28, vcc
	v_pk_mul_f32 v[28:29], v[18:19], v[28:29]
	v_lshlrev_b32_e32 v60, 16, v7
	v_pk_mul_f32 v[26:27], v[26:27], v[28:29]
	v_exp_f32_e32 v28, v6
	v_sub_f32_e32 v6, v40, v58
	v_mul_f32_e32 v6, 0x3fb8aa3b, v6
	v_exp_f32_e32 v29, v6
	v_mul_f32_e64 v6, |v60|, s26
	v_exp_f32_e32 v6, v6
	v_and_b32_e32 v61, 0xffff0000, v7
	v_cmp_le_f32_e32 vcc, 0, v60
	v_cmp_le_f32_e64 s[42:43], 0, v61
	v_add_f32_e32 v7, 1.0, v6
	v_rcp_f32_e32 v58, v7
	v_mul_f32_e64 v7, |v61|, s26
	v_exp_f32_e32 v7, v7
	v_cvt_pk_bf16_f32 v25, v4, v5
	v_cvt_pk_bf16_f32 v26, v26, v27
	v_add_f32_e32 v59, 1.0, v7
	v_rcp_f32_e32 v59, v59
	s_nop 0
	v_pk_mul_f32 v[6:7], v[6:7], v[58:59]
	s_nop 0
	v_cndmask_b32_e64 v7, v59, v7, s[42:43]
	v_cndmask_b32_e32 v6, v58, v6, vcc
	v_pk_mul_f32 v[6:7], v[16:17], v[6:7]
	v_add_co_u32_e32 v4, vcc, s13, v10
	v_pk_mul_f32 v[6:7], v[28:29], v[6:7]
	s_nop 0
	v_addc_co_u32_e32 v5, vcc, 0, v11, vcc
	v_cvt_pk_bf16_f32 v27, v6, v7
	ds_write_b128 v49, v[24:27] offset:11520
	v_mov_b64_e32 v[4:5], v[230:231]
	v_mov_b64_e32 v[6:7], v[232:233]
	v_sub_f32_e32 v25, v31, v56
	v_sub_f32_e32 v24, v1, v57
	v_mul_f32_e32 v24, 0x3fb8aa3b, v24
	v_mul_f32_e32 v25, 0x3fb8aa3b, v25
	v_exp_f32_e32 v24, v24
	v_exp_f32_e32 v25, v25
	s_waitcnt vmcnt(0) lgkmcnt(0)
	v_lshlrev_b32_e32 v56, 16, v4
	v_mul_f32_e64 v26, |v56|, s26
	v_exp_f32_e32 v26, v26
	v_and_b32_e32 v4, 0xffff0000, v4
	v_cmp_le_f32_e32 vcc, 0, v56
	v_cmp_le_f32_e64 s[42:43], 0, v4
	v_add_f32_e32 v27, 1.0, v26
	v_rcp_f32_e32 v28, v27
	v_mul_f32_e64 v27, |v4|, s26
	v_exp_f32_e32 v27, v27
	v_sub_f32_e32 v4, v36, v55
	v_mul_f32_e32 v4, 0x3fb8aa3b, v4
	v_and_b32_e32 v55, 0xffff0000, v5
	v_add_f32_e32 v29, 1.0, v27
	v_rcp_f32_e32 v29, v29
	s_nop 0
	v_pk_mul_f32 v[26:27], v[26:27], v[28:29]
	s_nop 0
	v_cndmask_b32_e64 v27, v29, v27, s[42:43]
	v_cndmask_b32_e32 v26, v28, v26, vcc
	v_pk_mul_f32 v[26:27], v[22:23], v[26:27]
	v_cmp_le_f32_e64 s[42:43], 0, v55
	v_pk_mul_f32 v[24:25], v[24:25], v[26:27]
	v_exp_f32_e32 v26, v4
	v_sub_f32_e32 v4, v38, v54
	v_mul_f32_e32 v4, 0x3fb8aa3b, v4
	v_lshlrev_b32_e32 v54, 16, v5
	v_exp_f32_e32 v27, v4
	v_mul_f32_e64 v4, |v54|, s26
	v_exp_f32_e32 v4, v4
	v_cmp_le_f32_e32 vcc, 0, v54
	v_lshlrev_b32_e32 v54, 16, v6
	v_and_b32_e32 v6, 0xffff0000, v6
	v_add_f32_e32 v5, 1.0, v4
	v_rcp_f32_e32 v28, v5
	v_mul_f32_e64 v5, |v55|, s26
	v_exp_f32_e32 v5, v5
	v_cvt_pk_bf16_f32 v24, v24, v25
	v_add_f32_e32 v29, 1.0, v5
	v_rcp_f32_e32 v29, v29
	s_nop 0
	v_pk_mul_f32 v[4:5], v[4:5], v[28:29]
	s_nop 0
	v_cndmask_b32_e32 v4, v28, v4, vcc
	v_mul_f32_e64 v28, |v54|, s26
	v_exp_f32_e32 v28, v28
	v_cndmask_b32_e64 v5, v29, v5, s[42:43]
	v_pk_mul_f32 v[4:5], v[20:21], v[4:5]
	v_cmp_le_f32_e32 vcc, 0, v54
	v_add_f32_e32 v29, 1.0, v28
	v_pk_mul_f32 v[4:5], v[26:27], v[4:5]
	v_sub_f32_e32 v27, v37, v52
	v_rcp_f32_e32 v52, v29
	v_mul_f32_e64 v29, |v6|, s26
	v_exp_f32_e32 v29, v29
	v_sub_f32_e32 v26, v35, v53
	v_mul_f32_e32 v26, 0x3fb8aa3b, v26
	v_mul_f32_e32 v27, 0x3fb8aa3b, v27
	v_add_f32_e32 v53, 1.0, v29
	v_rcp_f32_e32 v53, v53
	v_exp_f32_e32 v26, v26
	v_exp_f32_e32 v27, v27
	v_cmp_le_f32_e64 s[42:43], 0, v6
	v_pk_mul_f32 v[28:29], v[28:29], v[52:53]
	v_sub_f32_e32 v6, v39, v51
	v_cndmask_b32_e64 v29, v53, v29, s[42:43]
	v_cndmask_b32_e32 v28, v52, v28, vcc
	v_pk_mul_f32 v[28:29], v[18:19], v[28:29]
	v_mul_f32_e32 v6, 0x3fb8aa3b, v6
	v_pk_mul_f32 v[26:27], v[26:27], v[28:29]
	v_exp_f32_e32 v28, v6
	v_sub_f32_e32 v6, v40, v50
	v_mul_f32_e32 v6, 0x3fb8aa3b, v6
	v_lshlrev_b32_e32 v52, 16, v7
	v_exp_f32_e32 v29, v6
	v_mul_f32_e64 v6, |v52|, s26
	v_exp_f32_e32 v6, v6
	v_and_b32_e32 v53, 0xffff0000, v7
	v_cmp_le_f32_e32 vcc, 0, v52
	v_cmp_le_f32_e64 s[42:43], 0, v53
	v_add_f32_e32 v7, 1.0, v6
	v_rcp_f32_e32 v50, v7
	v_mul_f32_e64 v7, |v53|, s26
	v_exp_f32_e32 v7, v7
	v_cvt_pk_bf16_f32 v25, v4, v5
	v_cvt_pk_bf16_f32 v26, v26, v27
	v_add_f32_e32 v51, 1.0, v7
	v_rcp_f32_e32 v51, v51
	s_nop 0
	v_pk_mul_f32 v[6:7], v[6:7], v[50:51]
	s_nop 0
	v_cndmask_b32_e64 v7, v51, v7, s[42:43]
	v_cndmask_b32_e32 v6, v50, v6, vcc
	v_pk_mul_f32 v[6:7], v[16:17], v[6:7]
	v_add_co_u32_e32 v4, vcc, s33, v10
	v_pk_mul_f32 v[6:7], v[28:29], v[6:7]
	s_nop 0
	v_addc_co_u32_e32 v5, vcc, 0, v11, vcc
	v_cvt_pk_bf16_f32 v27, v6, v7
	ds_write_b128 v49, v[24:27] offset:13824
	v_mov_b64_e32 v[4:5], v[234:235]
	v_mov_b64_e32 v[6:7], v[236:237]
	v_sub_f32_e32 v25, v31, v47
	v_sub_f32_e32 v24, v1, v48
	v_mul_f32_e32 v24, 0x3fb8aa3b, v24
	v_mul_f32_e32 v25, 0x3fb8aa3b, v25
	v_exp_f32_e32 v24, v24
	v_exp_f32_e32 v25, v25
	s_waitcnt vmcnt(0) lgkmcnt(0)
; #define LAS __attribute__((address_space(3)))
; __device__ __forceinline__ u32x4 pack8(const float (&v)[8]) { u32x4 w; w.x = pk2(v[0], v[1]); w.y = pk2(v[2], v[3]); w.z = pk2(v[4], v[5]); w.w = pk2(v[6], v[7]); return w; }
; __device__ __forceinline__ void ld8bf(const bf16_t* p, float (&o)[8]) { unpack8(*(const u32x4*)p, o); }
; __device__ __forceinline__ void hg_lf_key(float fp, float lb, float& lf, float& key) {
;     const float e = __expf(-fabsf(fp));
;     const float rc = __builtin_amdgcn_rcpf(1.0f + e);
;     const float sp = fp >= 0.f ? rc : e * rc;
;     const float sn = fp >= 0.f ? e * rc : rc;
;     const float lsig = (fp >= 0.f ? 0.f : fp) + __logf(rc);
;     lf = (lb == 0.f) ? lsig : __logf(lb + (1.0f - lb) * sp); key = (1.0f - lb) * sn;
; }
; __device__ __forceinline__ void w_hg_m1(const Args& a, int l, unsigned char* ws, const bf16_t* proj, LAS unsigned char* wl, int b, int ck_, int h, int lane) {
;     ...
;         for (int tb = 0; tb < 4; ++tb) { float fp[8]; ld8bf(fsrc + (size_t)(16 * tb + lo) * NIN, fp);
;             float kb[8];
; #pragma unroll
;             for (int j = 0; j < 8; ++j) { float lf, key; hg_lf_key(fp[j], lbv[j], lf, key); kb[j] = key * __expf(r63[j] - bb[tb][j]); }
;             *(LAS u32x4*)(kT + (16 * tb + lo) * LD + 32 * kk + 8 * fq) = pack8(kb); }
;         if (lo == 0) { float* dp = (float*)(ws + WS_HGDEC) + (size_t)((b * NCH + ck_) * 4 + h) * 64 + 32 * kk + 8 * fq;
; #pragma unroll
;             for (int j = 0; j < 8; ++j) dp[j] = __expf(r63[j]); }
	v_lshlrev_b32_e32 v47, 16, v4
	v_mul_f32_e64 v26, |v47|, s26
	v_exp_f32_e32 v26, v26
	v_and_b32_e32 v4, 0xffff0000, v4
	v_cmp_le_f32_e32 vcc, 0, v47
	v_cmp_le_f32_e64 s[42:43], 0, v4
	v_add_f32_e32 v27, 1.0, v26
	v_rcp_f32_e32 v28, v27
	v_mul_f32_e64 v27, |v4|, s26
	v_exp_f32_e32 v27, v27
	v_sub_f32_e32 v4, v36, v46
	v_mul_f32_e32 v4, 0x3fb8aa3b, v4
	v_add_f32_e32 v29, 1.0, v27
	v_rcp_f32_e32 v29, v29
	s_nop 0
	v_pk_mul_f32 v[26:27], v[26:27], v[28:29]
	s_nop 0
	v_cndmask_b32_e64 v27, v29, v27, s[42:43]
	v_cndmask_b32_e32 v26, v28, v26, vcc
	v_pk_mul_f32 v[22:23], v[22:23], v[26:27]
	v_lshlrev_b32_e32 v28, 16, v5
	v_pk_mul_f32 v[22:23], v[24:25], v[22:23]
	v_exp_f32_e32 v24, v4
	v_sub_f32_e32 v4, v38, v45
	v_mul_f32_e32 v4, 0x3fb8aa3b, v4
	v_exp_f32_e32 v25, v4
	v_mul_f32_e64 v4, |v28|, s26
	v_exp_f32_e32 v4, v4
	v_and_b32_e32 v29, 0xffff0000, v5
	v_cmp_le_f32_e32 vcc, 0, v28
	v_cmp_le_f32_e64 s[42:43], 0, v29
	v_add_f32_e32 v5, 1.0, v4
	v_rcp_f32_e32 v26, v5
	v_mul_f32_e64 v5, |v29|, s26
	v_exp_f32_e32 v5, v5
	v_lshlrev_b32_e32 v28, 16, v6
	v_and_b32_e32 v6, 0xffff0000, v6
	v_add_f32_e32 v27, 1.0, v5
	v_rcp_f32_e32 v27, v27
	s_nop 0
	v_pk_mul_f32 v[4:5], v[4:5], v[26:27]
	s_nop 0
	v_cndmask_b32_e64 v5, v27, v5, s[42:43]
	v_cndmask_b32_e32 v4, v26, v4, vcc
	v_pk_mul_f32 v[4:5], v[20:21], v[4:5]
	v_sub_f32_e32 v20, v35, v44
	v_pk_mul_f32 v[4:5], v[24:25], v[4:5]
	v_mul_f32_e64 v24, |v28|, s26
	v_exp_f32_e32 v24, v24
	v_sub_f32_e32 v21, v37, v43
	v_mul_f32_e32 v20, 0x3fb8aa3b, v20
	v_mul_f32_e32 v21, 0x3fb8aa3b, v21
	v_add_f32_e32 v25, 1.0, v24
	v_rcp_f32_e32 v26, v25
	v_mul_f32_e64 v25, |v6|, s26
	v_exp_f32_e32 v25, v25
	v_exp_f32_e32 v20, v20
	v_exp_f32_e32 v21, v21
	v_cmp_le_f32_e32 vcc, 0, v28
	v_add_f32_e32 v27, 1.0, v25
	v_rcp_f32_e32 v27, v27
	v_cmp_le_f32_e64 s[42:43], 0, v6
	v_sub_f32_e32 v6, v39, v42
	v_mul_f32_e32 v6, 0x3fb8aa3b, v6
	v_pk_mul_f32 v[24:25], v[24:25], v[26:27]
	s_nop 0
	v_cndmask_b32_e64 v25, v27, v25, s[42:43]
	v_cndmask_b32_e32 v24, v26, v24, vcc
	v_pk_mul_f32 v[18:19], v[18:19], v[24:25]
	v_lshlrev_b32_e32 v26, 16, v7
	v_pk_mul_f32 v[18:19], v[20:21], v[18:19]
	v_exp_f32_e32 v20, v6
	v_sub_f32_e32 v6, v40, v41
	v_mul_f32_e32 v6, 0x3fb8aa3b, v6
	v_exp_f32_e32 v21, v6
	v_mul_f32_e64 v6, |v26|, s26
	v_exp_f32_e32 v6, v6
	v_and_b32_e32 v27, 0xffff0000, v7
	v_cmp_le_f32_e32 vcc, 0, v26
	v_cmp_le_f32_e64 s[42:43], 0, v27
	v_add_f32_e32 v7, 1.0, v6
	v_rcp_f32_e32 v24, v7
	v_mul_f32_e64 v7, |v27|, s26
	v_exp_f32_e32 v7, v7
	v_cvt_pk_bf16_f32 v18, v18, v19
	v_add_f32_e32 v25, 1.0, v7
	v_rcp_f32_e32 v25, v25
	s_nop 0
	v_pk_mul_f32 v[6:7], v[6:7], v[24:25]
	s_nop 0
	v_cndmask_b32_e64 v7, v25, v7, s[42:43]
	v_cndmask_b32_e32 v6, v24, v6, vcc
	v_pk_mul_f32 v[6:7], v[16:17], v[6:7]
	v_cvt_pk_bf16_f32 v16, v22, v23
	v_pk_mul_f32 v[6:7], v[20:21], v[6:7]
	v_cvt_pk_bf16_f32 v17, v4, v5
	v_cvt_pk_bf16_f32 v19, v6, v7
	ds_write_b128 v49, v[16:19] offset:16128
	s_and_saveexec_b64 s[34:35], s[38:39]
	s_cbranch_execz .LBB0_671
	v_mul_f32_e32 v1, 0x3fb8aa3b, v1
	v_exp_f32_e32 v4, v1
	v_mul_f32_e32 v1, 0x3fb8aa3b, v31
	v_exp_f32_e32 v5, v1
	v_mul_f32_e32 v1, 0x3fb8aa3b, v36
	v_exp_f32_e32 v6, v1
	v_mul_f32_e32 v1, 0x3fb8aa3b, v38
	v_exp_f32_e32 v7, v1
	v_mul_f32_e32 v1, 0x3fb8aa3b, v35
	flat_store_dwordx4 v[8:9], v[4:7]
	s_nop 1
	v_exp_f32_e32 v4, v1
	v_mul_f32_e32 v1, 0x3fb8aa3b, v37
	v_exp_f32_e32 v5, v1
	v_mul_f32_e32 v1, 0x3fb8aa3b, v39
	v_exp_f32_e32 v6, v1
	v_mul_f32_e32 v1, 0x3fb8aa3b, v40
	v_exp_f32_e32 v7, v1
	flat_store_dwordx4 v[8:9], v[4:7] offset:16

; __device__ __forceinline__ void ld8bf(const bf16_t* p, float (&o)[8]) { unpack8(*(const u32x4*)p, o); }
; __device__ __forceinline__ void hg_lf_key(float fp, float lb, float& lf, float& key) {
;     const float e = __expf(-fabsf(fp));
;     const float rc = __builtin_amdgcn_rcpf(1.0f + e);
;     const float sp = fp >= 0.f ? rc : e * rc;
;     const float sn = fp >= 0.f ? e * rc : rc;
;     const float lsig = (fp >= 0.f ? 0.f : fp) + __logf(rc);
;     lf = (lb == 0.f) ? lsig : __logf(lb + (1.0f - lb) * sp); key = (1.0f - lb) * sn;
; }
; __device__ __forceinline__ void w_hg_scan(const float (&lbv)[8], const bf16_t* fsrc, int lane, float (&bb)[4][8], float (&r31)[8], float (&r63)[8]) {
;     ...
;     for (int tb = 0; tb < 4; ++tb) { float fp[8]; ld8bf(fsrc + (size_t)(16 * tb + lo) * NIN, fp);
; #pragma unroll
;         for (int j = 0; j < 8; ++j) { float key; hg_lf_key(fp[j], lbv[j], bb[tb][j], key); } }
.LBB0_680:
	v_mov_b64_e32 v[4:5], v[238:239]
	v_mov_b64_e32 v[6:7], v[240:241]
	v_cmp_neq_f32_e64 s[40:41], 0, v20
	v_sub_f32_e32 v35, 1.0, v20
	s_waitcnt vmcnt(0) lgkmcnt(0)
	v_lshlrev_b32_e32 v12, 16, v4
	v_mul_f32_e64 v13, |v12|, s26
	v_exp_f32_e32 v24, v13
	v_cmp_le_f32_e32 vcc, 0, v12
	v_add_f32_e32 v13, 1.0, v24
	v_rcp_f32_e32 v13, v13
	s_and_saveexec_b64 s[20:21], s[40:41]
	s_xor_b64 s[34:35], exec, s[20:21]
	s_cbranch_execz .LBB0_682
	v_mul_f32_e32 v12, v24, v13
	v_cndmask_b32_e32 v12, v12, v13, vcc
	v_fma_f32 v12, v35, v12, v20
	v_cmp_gt_f32_e64 s[42:43], s29, v12
	s_nop 1
	v_cndmask_b32_e64 v13, 0, 32, s[42:43]
	v_ldexp_f32 v12, v12, v13
	v_log_f32_e32 v12, v12
	s_nop 0
	v_mul_f32_e32 v13, 0x3f317217, v12
	v_fma_f32 v13, v12, s17, -v13
	v_fmac_f32_e32 v13, 0x3377d1cf, v12
	v_fmac_f32_e32 v13, 0x3f317217, v12
	v_cmp_lt_f32_e64 s[44:45], |v12|, s22
	s_nop 1
	v_cndmask_b32_e64 v12, v12, v13, s[44:45]
	v_cndmask_b32_e64 v13, 0, v203, s[42:43]
	v_sub_f32_e32 v22, v12, v13

; __device__ __forceinline__ void ld8bf(const bf16_t* p, float (&o)[8]) { unpack8(*(const u32x4*)p, o); }
; __device__ __forceinline__ void hg_lf_key(float fp, float lb, float& lf, float& key) {
;     const float e = __expf(-fabsf(fp));
;     const float rc = __builtin_amdgcn_rcpf(1.0f + e);
;     const float sp = fp >= 0.f ? rc : e * rc;
;     const float sn = fp >= 0.f ? e * rc : rc;
;     const float lsig = (fp >= 0.f ? 0.f : fp) + __logf(rc);
;     lf = (lb == 0.f) ? lsig : __logf(lb + (1.0f - lb) * sp); key = (1.0f - lb) * sn;
; }
; __device__ __forceinline__ void w_hg_scan(const float (&lbv)[8], const bf16_t* fsrc, int lane, float (&bb)[4][8], float (&r31)[8], float (&r63)[8]) {
;     ...
;     for (int tb = 0; tb < 4; ++tb) { float fp[8]; ld8bf(fsrc + (size_t)(16 * tb + lo) * NIN, fp);
; #pragma unroll
;         for (int j = 0; j < 8; ++j) { float key; hg_lf_key(fp[j], lbv[j], bb[tb][j], key); } }
.LBB0_712:
	s_or_b64 exec, exec, s[34:35]
	v_lshl_add_u64 v[14:15], v[14:15], 0, 64
	v_add_co_u32_e32 v4, vcc, 0x18000, v14
	s_nop 1
	v_addc_co_u32_e32 v5, vcc, 0, v15, vcc
	v_mov_b64_e32 v[4:5], v[242:243]
	v_mov_b64_e32 v[6:7], v[244:245]
	s_waitcnt vmcnt(0) lgkmcnt(0)
	v_lshlrev_b32_e32 v42, 16, v4
	v_mul_f32_e64 v41, |v42|, s26
	v_exp_f32_e32 v44, v41
	v_cmp_le_f32_e32 vcc, 0, v42
	v_add_f32_e32 v41, 1.0, v44
	v_rcp_f32_e32 v43, v41
	s_and_saveexec_b64 s[20:21], s[40:41]
	s_xor_b64 s[34:35], exec, s[20:21]
	s_cbranch_execz .LBB0_714
	v_mul_f32_e32 v41, v44, v43
	v_cndmask_b32_e32 v41, v41, v43, vcc
	v_fma_f32 v41, v35, v41, v20
	v_cmp_gt_f32_e64 s[56:57], s29, v41
	s_nop 1
	v_cndmask_b32_e64 v42, 0, 32, s[56:57]
	v_ldexp_f32 v41, v41, v42
	v_log_f32_e32 v41, v41
	s_nop 0
	v_mul_f32_e32 v42, 0x3f317217, v41
	v_fma_f32 v42, v41, s17, -v42
	v_fmac_f32_e32 v42, 0x3377d1cf, v41
	v_fmac_f32_e32 v42, 0x3f317217, v41
	v_cmp_lt_f32_e64 s[58:59], |v41|, s22
	s_nop 1
	v_cndmask_b32_e64 v41, v41, v42, s[58:59]
	v_cndmask_b32_e64 v42, 0, v203, s[56:57]
	v_sub_f32_e32 v41, v41, v42

; __device__ __forceinline__ void ld8bf(const bf16_t* p, float (&o)[8]) { unpack8(*(const u32x4*)p, o); }
; __device__ __forceinline__ void hg_lf_key(float fp, float lb, float& lf, float& key) {
;     const float e = __expf(-fabsf(fp));
;     const float rc = __builtin_amdgcn_rcpf(1.0f + e);
;     const float sp = fp >= 0.f ? rc : e * rc;
;     const float sn = fp >= 0.f ? e * rc : rc;
;     const float lsig = (fp >= 0.f ? 0.f : fp) + __logf(rc);
;     lf = (lb == 0.f) ? lsig : __logf(lb + (1.0f - lb) * sp); key = (1.0f - lb) * sn;
; }
; __device__ __forceinline__ void w_hg_scan(const float (&lbv)[8], const bf16_t* fsrc, int lane, float (&bb)[4][8], float (&r31)[8], float (&r63)[8]) {
;     ...
;     for (int tb = 0; tb < 4; ++tb) { float fp[8]; ld8bf(fsrc + (size_t)(16 * tb + lo) * NIN, fp);
; #pragma unroll
;         for (int j = 0; j < 8; ++j) { float key; hg_lf_key(fp[j], lbv[j], bb[tb][j], key); } }
.LBB0_744:
	s_or_b64 exec, exec, s[34:35]
	v_add_co_u32_e32 v4, vcc, 0x30000, v14
	s_nop 1
	v_addc_co_u32_e32 v5, vcc, 0, v15, vcc
	v_mov_b64_e32 v[4:5], v[246:247]
	v_mov_b64_e32 v[6:7], v[248:249]
	s_waitcnt vmcnt(0) lgkmcnt(0)
	v_lshlrev_b32_e32 v50, 16, v4
	v_mul_f32_e64 v49, |v50|, s26
	v_exp_f32_e32 v52, v49
	v_cmp_le_f32_e32 vcc, 0, v50
	v_add_f32_e32 v49, 1.0, v52
	v_rcp_f32_e32 v51, v49
	s_and_saveexec_b64 s[20:21], s[40:41]
	s_xor_b64 s[34:35], exec, s[20:21]
	s_cbranch_execz .LBB0_746
	v_mul_f32_e32 v49, v52, v51
	v_cndmask_b32_e32 v49, v49, v51, vcc
	v_fma_f32 v49, v35, v49, v20
	v_cmp_gt_f32_e64 s[56:57], s29, v49
	s_nop 1
	v_cndmask_b32_e64 v50, 0, 32, s[56:57]
	v_ldexp_f32 v49, v49, v50
	v_log_f32_e32 v49, v49
	s_nop 0
	v_mul_f32_e32 v50, 0x3f317217, v49
	v_fma_f32 v50, v49, s17, -v50
	v_fmac_f32_e32 v50, 0x3377d1cf, v49
	v_fmac_f32_e32 v50, 0x3f317217, v49
	v_cmp_lt_f32_e64 s[58:59], |v49|, s22
	s_nop 1
	v_cndmask_b32_e64 v49, v49, v50, s[58:59]
	v_cndmask_b32_e64 v50, 0, v203, s[56:57]
	v_sub_f32_e32 v49, v49, v50

; __device__ __forceinline__ void ld8bf(const bf16_t* p, float (&o)[8]) { unpack8(*(const u32x4*)p, o); }
; __device__ __forceinline__ void hg_lf_key(float fp, float lb, float& lf, float& key) {
;     const float e = __expf(-fabsf(fp));
;     const float rc = __builtin_amdgcn_rcpf(1.0f + e);
;     const float sp = fp >= 0.f ? rc : e * rc;
;     const float sn = fp >= 0.f ? e * rc : rc;
;     const float lsig = (fp >= 0.f ? 0.f : fp) + __logf(rc);
;     lf = (lb == 0.f) ? lsig : __logf(lb + (1.0f - lb) * sp); key = (1.0f - lb) * sn;
; }
; __device__ __forceinline__ void w_hg_scan(const float (&lbv)[8], const bf16_t* fsrc, int lane, float (&bb)[4][8], float (&r31)[8], float (&r63)[8]) {
;     ...
;     for (int tb = 0; tb < 4; ++tb) { float fp[8]; ld8bf(fsrc + (size_t)(16 * tb + lo) * NIN, fp);
; #pragma unroll
;         for (int j = 0; j < 8; ++j) { float key; hg_lf_key(fp[j], lbv[j], bb[tb][j], key); } }
.LBB0_776:
	s_or_b64 exec, exec, s[34:35]
	v_add_co_u32_e32 v4, vcc, 0x48000, v14
	s_nop 1
	v_addc_co_u32_e32 v5, vcc, 0, v15, vcc
	v_mov_b64_e32 v[4:5], v[250:251]
	v_mov_b64_e32 v[6:7], v[252:253]
	s_waitcnt vmcnt(0) lgkmcnt(0)
	v_lshlrev_b32_e32 v54, 16, v4
	v_mul_f32_e64 v55, |v54|, s26
	v_exp_f32_e32 v56, v55
	v_cmp_le_f32_e32 vcc, 0, v54
	v_add_f32_e32 v55, 1.0, v56
	v_rcp_f32_e32 v55, v55
	s_and_saveexec_b64 s[20:21], s[40:41]
	s_xor_b64 s[34:35], exec, s[20:21]
	s_cbranch_execz .LBB0_778
	v_mul_f32_e32 v54, v56, v55
	v_cndmask_b32_e32 v54, v54, v55, vcc
	v_fma_f32 v35, v35, v54, v20
	v_cmp_gt_f32_e64 s[40:41], s29, v35
	s_nop 1
	v_cndmask_b32_e64 v54, 0, 32, s[40:41]
	v_ldexp_f32 v35, v35, v54
	v_log_f32_e32 v35, v35
	s_nop 0
	v_mul_f32_e32 v54, 0x3f317217, v35
	v_fma_f32 v54, v35, s17, -v54
	v_fmac_f32_e32 v54, 0x3377d1cf, v35
	v_fmac_f32_e32 v54, 0x3f317217, v35
	v_cmp_lt_f32_e64 s[56:57], |v35|, s22
	s_nop 1
	v_cndmask_b32_e64 v35, v35, v54, s[56:57]
	v_cndmask_b32_e64 v54, 0, v203, s[40:41]
	v_sub_f32_e32 v67, v35, v54

; __device__ __forceinline__ float bperm_f(int src_lane, float v) { return __builtin_bit_cast(float, __builtin_amdgcn_ds_bpermute(src_lane << 2, __builtin_bit_cast(int, v))); }
; __device__ __forceinline__ float row_sum_incl(float v) { v += dpp_shr0<1>(v); v += dpp_shr0<2>(v); v += dpp_shr0<4>(v); v += dpp_shr0<8>(v); return v; }
; __device__ __forceinline__ float bcast15(float v, int lane) { return bperm_f((lane & 48) | 15, v); }
; __device__ __forceinline__ void w_hg_scan(const float (&lbv)[8], const bf16_t* fsrc, int lane, float (&bb)[4][8], float (&r31)[8], float (&r63)[8]) {
;     ...
;     for (int tb = 0; tb < 4; ++tb) {
; #pragma unroll
;         for (int j = 0; j < 8; ++j) { const float v = row_sum_incl(bb[tb][j]) + carry[j]; bb[tb][j] = v; carry[j] = bcast15(v, lane); if (tb == 1) r31[j] = carry[j]; if (tb == 3) r63[j] = carry[j]; }
;         __builtin_amdgcn_sched_barrier(0);
;     }
; }
.LBB0_808:
	s_or_b64 exec, exec, s[34:35]
	v_add_f32_dpp v1, v22, v22 row_shr:1 row_mask:0xf bank_mask:0xf bound_ctrl:1
	v_add_f32_dpp v22, v24, v24 row_shr:1 row_mask:0xf bank_mask:0xf bound_ctrl:1
	v_or_b32_e32 v30, 60, v30
	v_add_f32_dpp v1, v1, v1 row_shr:2 row_mask:0xf bank_mask:0xf bound_ctrl:1
	v_add_f32_dpp v22, v22, v22 row_shr:2 row_mask:0xf bank_mask:0xf bound_ctrl:1
	s_mov_b64 s[20:21], 0x18000
	v_add_f32_dpp v1, v1, v1 row_shr:4 row_mask:0xf bank_mask:0xf bound_ctrl:1
	v_add_f32_dpp v22, v22, v22 row_shr:4 row_mask:0xf bank_mask:0xf bound_ctrl:1
	v_mul_u32_u24_e32 v68, 0x90, v34
	v_add_f32_dpp v1, v1, v1 row_shr:8 row_mask:0xf bank_mask:0xf bound_ctrl:1
	v_add_f32_dpp v22, v22, v22 row_shr:8 row_mask:0xf bank_mask:0xf bound_ctrl:1
	v_add_f32_e32 v72, 0, v22
	v_add_f32_e32 v71, 0, v1
	v_add_f32_dpp v22, v25, v25 row_shr:1 row_mask:0xf bank_mask:0xf bound_ctrl:1
	ds_bpermute_b32 v1, v30, v71
	ds_bpermute_b32 v35, v30, v72
	v_add_f32_dpp v22, v22, v22 row_shr:2 row_mask:0xf bank_mask:0xf bound_ctrl:1
	v_lshl_add_u64 v[24:25], v[10:11], 0, s[20:21]
	s_mov_b64 s[20:21], 0x30000
	v_add_f32_dpp v22, v22, v22 row_shr:4 row_mask:0xf bank_mask:0xf bound_ctrl:1
	s_nop 1
	v_add_f32_dpp v22, v22, v22 row_shr:8 row_mask:0xf bank_mask:0xf bound_ctrl:1
	v_add_f32_e32 v73, 0, v22
	ds_bpermute_b32 v37, v30, v73
	v_add_f32_dpp v22, v26, v26 row_shr:1 row_mask:0xf bank_mask:0xf bound_ctrl:1
	s_nop 1
	v_add_f32_dpp v22, v22, v22 row_shr:2 row_mask:0xf bank_mask:0xf bound_ctrl:1
	s_nop 1
	v_add_f32_dpp v22, v22, v22 row_shr:4 row_mask:0xf bank_mask:0xf bound_ctrl:1
	s_nop 1
	v_add_f32_dpp v22, v22, v22 row_shr:8 row_mask:0xf bank_mask:0xf bound_ctrl:1
	v_add_f32_e32 v26, 0, v22
	ds_bpermute_b32 v39, v30, v26
	v_add_f32_dpp v22, v27, v27 row_shr:1 row_mask:0xf bank_mask:0xf bound_ctrl:1
	s_nop 1
	v_add_f32_dpp v22, v22, v22 row_shr:2 row_mask:0xf bank_mask:0xf bound_ctrl:1
	s_nop 1
	v_add_f32_dpp v22, v22, v22 row_shr:4 row_mask:0xf bank_mask:0xf bound_ctrl:1
	s_nop 1
	v_add_f32_dpp v22, v22, v22 row_shr:8 row_mask:0xf bank_mask:0xf bound_ctrl:1
	v_add_f32_e32 v27, 0, v22
	ds_bpermute_b32 v54, v30, v27
	v_add_f32_dpp v22, v28, v28 row_shr:1 row_mask:0xf bank_mask:0xf bound_ctrl:1
	s_nop 1
	v_add_f32_dpp v22, v22, v22 row_shr:2 row_mask:0xf bank_mask:0xf bound_ctrl:1
	s_nop 1
	v_add_f32_dpp v22, v22, v22 row_shr:4 row_mask:0xf bank_mask:0xf bound_ctrl:1
	s_nop 1
	v_add_f32_dpp v22, v22, v22 row_shr:8 row_mask:0xf bank_mask:0xf bound_ctrl:1
	v_add_f32_e32 v28, 0, v22
	ds_bpermute_b32 v55, v30, v28
	v_add_f32_dpp v22, v29, v29 row_shr:1 row_mask:0xf bank_mask:0xf bound_ctrl:1
	s_nop 1
	v_add_f32_dpp v22, v22, v22 row_shr:2 row_mask:0xf bank_mask:0xf bound_ctrl:1
	s_nop 1
	v_add_f32_dpp v22, v22, v22 row_shr:4 row_mask:0xf bank_mask:0xf bound_ctrl:1
	s_nop 1
	v_add_f32_dpp v22, v22, v22 row_shr:8 row_mask:0xf bank_mask:0xf bound_ctrl:1
	v_add_f32_e32 v29, 0, v22
	ds_bpermute_b32 v56, v30, v29
	v_add_f32_dpp v22, v31, v31 row_shr:1 row_mask:0xf bank_mask:0xf bound_ctrl:1
	s_nop 1
	v_add_f32_dpp v22, v22, v22 row_shr:2 row_mask:0xf bank_mask:0xf bound_ctrl:1
	s_nop 1
	v_add_f32_dpp v22, v22, v22 row_shr:4 row_mask:0xf bank_mask:0xf bound_ctrl:1
	s_nop 1
	v_add_f32_dpp v22, v22, v22 row_shr:8 row_mask:0xf bank_mask:0xf bound_ctrl:1
	v_add_f32_e32 v31, 0, v22
	ds_bpermute_b32 v57, v30, v31
	v_lshl_add_u64 v[22:23], v[10:11], 0, s[20:21]
	v_add_f32_dpp v41, v41, v41 row_shr:1 row_mask:0xf bank_mask:0xf bound_ctrl:1
	s_nop 1
	v_add_f32_dpp v41, v41, v41 row_shr:2 row_mask:0xf bank_mask:0xf bound_ctrl:1
	s_nop 1
	v_add_f32_dpp v41, v41, v41 row_shr:4 row_mask:0xf bank_mask:0xf bound_ctrl:1
	s_nop 1
	v_add_f32_dpp v41, v41, v41 row_shr:8 row_mask:0xf bank_mask:0xf bound_ctrl:1
	s_waitcnt lgkmcnt(7)
	v_add_f32_e32 v70, v41, v1
	ds_bpermute_b32 v1, v30, v70
	v_add_f32_dpp v41, v42, v42 row_shr:1 row_mask:0xf bank_mask:0xf bound_ctrl:1
	v_add_f32_dpp v42, v46, v46 row_shr:1 row_mask:0xf bank_mask:0xf bound_ctrl:1
	s_nop 0
	v_add_f32_dpp v41, v41, v41 row_shr:2 row_mask:0xf bank_mask:0xf bound_ctrl:1
	v_add_f32_dpp v42, v42, v42 row_shr:2 row_mask:0xf bank_mask:0xf bound_ctrl:1
	s_nop 0
	v_add_f32_dpp v41, v41, v41 row_shr:4 row_mask:0xf bank_mask:0xf bound_ctrl:1
	v_add_f32_dpp v42, v42, v42 row_shr:4 row_mask:0xf bank_mask:0xf bound_ctrl:1
	s_nop 0
	v_add_f32_dpp v41, v41, v41 row_shr:8 row_mask:0xf bank_mask:0xf bound_ctrl:1
	s_waitcnt lgkmcnt(7)
	v_add_f32_e32 v69, v41, v35
	ds_bpermute_b32 v35, v30, v69
	v_add_f32_dpp v41, v43, v43 row_shr:1 row_mask:0xf bank_mask:0xf bound_ctrl:1
	v_add_f32_dpp v43, v47, v47 row_shr:1 row_mask:0xf bank_mask:0xf bound_ctrl:1
	v_add_f32_dpp v42, v42, v42 row_shr:8 row_mask:0xf bank_mask:0xf bound_ctrl:1
	v_add_f32_dpp v41, v41, v41 row_shr:2 row_mask:0xf bank_mask:0xf bound_ctrl:1
	v_add_f32_dpp v43, v43, v43 row_shr:2 row_mask:0xf bank_mask:0xf bound_ctrl:1
	s_waitcnt lgkmcnt(4)
	v_add_f32_e32 v62, v42, v55
	v_add_f32_dpp v41, v41, v41 row_shr:4 row_mask:0xf bank_mask:0xf bound_ctrl:1
	v_add_f32_dpp v43, v43, v43 row_shr:4 row_mask:0xf bank_mask:0xf bound_ctrl:1
	ds_bpermute_b32 v42, v30, v62
	v_add_f32_dpp v41, v41, v41 row_shr:8 row_mask:0xf bank_mask:0xf bound_ctrl:1
	v_add_f32_e32 v66, v41, v37
	ds_bpermute_b32 v37, v30, v66
	v_add_f32_dpp v41, v44, v44 row_shr:1 row_mask:0xf bank_mask:0xf bound_ctrl:1
	v_add_f32_dpp v44, v48, v48 row_shr:1 row_mask:0xf bank_mask:0xf bound_ctrl:1
	v_add_f32_dpp v43, v43, v43 row_shr:8 row_mask:0xf bank_mask:0xf bound_ctrl:1
	v_add_f32_dpp v41, v41, v41 row_shr:2 row_mask:0xf bank_mask:0xf bound_ctrl:1
	v_add_f32_dpp v44, v44, v44 row_shr:2 row_mask:0xf bank_mask:0xf bound_ctrl:1
	s_waitcnt lgkmcnt(5)
; __device__ __forceinline__ float bperm_f(int src_lane, float v) { return __builtin_bit_cast(float, __builtin_amdgcn_ds_bpermute(src_lane << 2, __builtin_bit_cast(int, v))); }
; __device__ __forceinline__ float row_sum_incl(float v) { v += dpp_shr0<1>(v); v += dpp_shr0<2>(v); v += dpp_shr0<4>(v); v += dpp_shr0<8>(v); return v; }
; __device__ __forceinline__ float bcast15(float v, int lane) { return bperm_f((lane & 48) | 15, v); }
; __device__ __forceinline__ void w_hg_scan(const float (&lbv)[8], const bf16_t* fsrc, int lane, float (&bb)[4][8], float (&r31)[8], float (&r63)[8]) {
;     ...
;     for (int tb = 0; tb < 4; ++tb) {
; #pragma unroll
;         for (int j = 0; j < 8; ++j) { const float v = row_sum_incl(bb[tb][j]) + carry[j]; bb[tb][j] = v; carry[j] = bcast15(v, lane); if (tb == 1) r31[j] = carry[j]; if (tb == 3) r63[j] = carry[j]; }
;         __builtin_amdgcn_sched_barrier(0);
;     }
; }
	v_add_f32_e32 v60, v43, v56
	v_add_f32_dpp v41, v41, v41 row_shr:4 row_mask:0xf bank_mask:0xf bound_ctrl:1
	v_add_f32_dpp v44, v44, v44 row_shr:4 row_mask:0xf bank_mask:0xf bound_ctrl:1
	ds_bpermute_b32 v43, v30, v60
	v_add_f32_dpp v41, v41, v41 row_shr:8 row_mask:0xf bank_mask:0xf bound_ctrl:1
	v_add_f32_e32 v65, v41, v39
	ds_bpermute_b32 v39, v30, v65
	v_add_f32_dpp v41, v45, v45 row_shr:1 row_mask:0xf bank_mask:0xf bound_ctrl:1
	v_add_f32_dpp v44, v44, v44 row_shr:8 row_mask:0xf bank_mask:0xf bound_ctrl:1
	s_waitcnt lgkmcnt(6)
	v_add_f32_e32 v59, v44, v57
	v_add_f32_dpp v41, v41, v41 row_shr:2 row_mask:0xf bank_mask:0xf bound_ctrl:1
	ds_bpermute_b32 v44, v30, v59
	s_nop 0
	v_add_f32_dpp v41, v41, v41 row_shr:4 row_mask:0xf bank_mask:0xf bound_ctrl:1
	s_nop 1
	v_add_f32_dpp v41, v41, v41 row_shr:8 row_mask:0xf bank_mask:0xf bound_ctrl:1
	v_add_f32_e32 v63, v41, v54
	ds_bpermute_b32 v41, v30, v63
	v_add_f32_dpp v45, v49, v49 row_shr:1 row_mask:0xf bank_mask:0xf bound_ctrl:1
	s_nop 1
	v_add_f32_dpp v45, v45, v45 row_shr:2 row_mask:0xf bank_mask:0xf bound_ctrl:1
	s_nop 1
	v_add_f32_dpp v45, v45, v45 row_shr:4 row_mask:0xf bank_mask:0xf bound_ctrl:1
	s_nop 1
	v_add_f32_dpp v45, v45, v45 row_shr:8 row_mask:0xf bank_mask:0xf bound_ctrl:1
	s_waitcnt lgkmcnt(7)
	v_add_f32_e32 v57, v45, v1
	ds_bpermute_b32 v1, v30, v57
	v_add_f32_dpp v45, v50, v50 row_shr:1 row_mask:0xf bank_mask:0xf bound_ctrl:1
	s_nop 1
	v_add_f32_dpp v45, v45, v45 row_shr:2 row_mask:0xf bank_mask:0xf bound_ctrl:1
	s_nop 1
	v_add_f32_dpp v45, v45, v45 row_shr:4 row_mask:0xf bank_mask:0xf bound_ctrl:1
	s_nop 1
	v_add_f32_dpp v45, v45, v45 row_shr:8 row_mask:0xf bank_mask:0xf bound_ctrl:1
	s_waitcnt lgkmcnt(7)
	v_add_f32_e32 v56, v45, v35
	ds_bpermute_b32 v35, v30, v56
	v_add_f32_dpp v45, v51, v51 row_shr:1 row_mask:0xf bank_mask:0xf bound_ctrl:1
	s_nop 1
	v_add_f32_dpp v45, v45, v45 row_shr:2 row_mask:0xf bank_mask:0xf bound_ctrl:1
	s_nop 1
	v_add_f32_dpp v45, v45, v45 row_shr:4 row_mask:0xf bank_mask:0xf bound_ctrl:1
	s_nop 1
	v_add_f32_dpp v45, v45, v45 row_shr:8 row_mask:0xf bank_mask:0xf bound_ctrl:1
	s_waitcnt lgkmcnt(6)
	v_add_f32_e32 v55, v45, v37
	ds_bpermute_b32 v37, v30, v55
	v_add_f32_dpp v45, v52, v52 row_shr:1 row_mask:0xf bank_mask:0xf bound_ctrl:1
	s_nop 1
	v_add_f32_dpp v45, v45, v45 row_shr:2 row_mask:0xf bank_mask:0xf bound_ctrl:1
	s_nop 1
	v_add_f32_dpp v45, v45, v45 row_shr:4 row_mask:0xf bank_mask:0xf bound_ctrl:1
	s_nop 1
	v_add_f32_dpp v45, v45, v45 row_shr:8 row_mask:0xf bank_mask:0xf bound_ctrl:1
	s_waitcnt lgkmcnt(5)
	v_add_f32_e32 v54, v45, v39
	ds_bpermute_b32 v39, v30, v54
	v_add_f32_dpp v45, v53, v53 row_shr:1 row_mask:0xf bank_mask:0xf bound_ctrl:1
	s_nop 1
	v_add_f32_dpp v45, v45, v45 row_shr:2 row_mask:0xf bank_mask:0xf bound_ctrl:1
	s_nop 1
	v_add_f32_dpp v45, v45, v45 row_shr:4 row_mask:0xf bank_mask:0xf bound_ctrl:1
	s_nop 1
	v_add_f32_dpp v45, v45, v45 row_shr:8 row_mask:0xf bank_mask:0xf bound_ctrl:1
	s_waitcnt lgkmcnt(4)
	v_add_f32_e32 v53, v45, v41
	ds_bpermute_b32 v41, v30, v53
	v_add_f32_dpp v45, v58, v58 row_shr:1 row_mask:0xf bank_mask:0xf bound_ctrl:1
	s_nop 1
	v_add_f32_dpp v45, v45, v45 row_shr:2 row_mask:0xf bank_mask:0xf bound_ctrl:1
	s_nop 1
	v_add_f32_dpp v45, v45, v45 row_shr:4 row_mask:0xf bank_mask:0xf bound_ctrl:1
	s_nop 1
	v_add_f32_dpp v45, v45, v45 row_shr:8 row_mask:0xf bank_mask:0xf bound_ctrl:1
	v_add_f32_e32 v52, v45, v42
	ds_bpermute_b32 v42, v30, v52
	v_add_f32_dpp v45, v61, v61 row_shr:1 row_mask:0xf bank_mask:0xf bound_ctrl:1
	s_nop 1
	v_add_f32_dpp v45, v45, v45 row_shr:2 row_mask:0xf bank_mask:0xf bound_ctrl:1
	s_nop 1
	v_add_f32_dpp v45, v45, v45 row_shr:4 row_mask:0xf bank_mask:0xf bound_ctrl:1
	s_nop 1
	v_add_f32_dpp v45, v45, v45 row_shr:8 row_mask:0xf bank_mask:0xf bound_ctrl:1
	v_add_f32_e32 v51, v45, v43
	ds_bpermute_b32 v43, v30, v51
	v_add_f32_dpp v45, v64, v64 row_shr:1 row_mask:0xf bank_mask:0xf bound_ctrl:1
	s_nop 1
	v_add_f32_dpp v45, v45, v45 row_shr:2 row_mask:0xf bank_mask:0xf bound_ctrl:1
	s_nop 1
	v_add_f32_dpp v45, v45, v45 row_shr:4 row_mask:0xf bank_mask:0xf bound_ctrl:1
	s_nop 1
	v_add_f32_dpp v45, v45, v45 row_shr:8 row_mask:0xf bank_mask:0xf bound_ctrl:1
	v_add_f32_e32 v50, v45, v44
	ds_bpermute_b32 v58, v30, v50
	v_add_f32_dpp v4, v4, v4 row_shr:1 row_mask:0xf bank_mask:0xf bound_ctrl:1
	v_add_f32_dpp v44, v67, v67 row_shr:1 row_mask:0xf bank_mask:0xf bound_ctrl:1
	s_nop 0
	v_add_f32_dpp v4, v4, v4 row_shr:2 row_mask:0xf bank_mask:0xf bound_ctrl:1
	v_add_f32_dpp v44, v44, v44 row_shr:2 row_mask:0xf bank_mask:0xf bound_ctrl:1
	s_nop 0
	v_add_f32_dpp v4, v4, v4 row_shr:4 row_mask:0xf bank_mask:0xf bound_ctrl:1
	v_add_f32_dpp v44, v44, v44 row_shr:4 row_mask:0xf bank_mask:0xf bound_ctrl:1
	s_nop 0
	v_add_f32_dpp v4, v4, v4 row_shr:8 row_mask:0xf bank_mask:0xf bound_ctrl:1
	s_waitcnt lgkmcnt(6)
	v_add_f32_e32 v48, v4, v35
	v_add_f32_dpp v44, v44, v44 row_shr:8 row_mask:0xf bank_mask:0xf bound_ctrl:1
	v_add_f32_dpp v4, v36, v36 row_shr:1 row_mask:0xf bank_mask:0xf bound_ctrl:1
	v_add_f32_e32 v49, v44, v1
	ds_bpermute_b32 v1, v30, v49
	v_add_f32_dpp v4, v4, v4 row_shr:2 row_mask:0xf bank_mask:0xf bound_ctrl:1
	ds_bpermute_b32 v35, v30, v48
	s_nop 0
	v_add_f32_dpp v4, v4, v4 row_shr:4 row_mask:0xf bank_mask:0xf bound_ctrl:1
	s_nop 1
	v_add_f32_dpp v4, v4, v4 row_shr:8 row_mask:0xf bank_mask:0xf bound_ctrl:1
	s_waitcnt lgkmcnt(7)
	v_add_f32_e32 v47, v4, v37
	ds_bpermute_b32 v37, v30, v47
	v_add_f32_dpp v4, v5, v5 row_shr:1 row_mask:0xf bank_mask:0xf bound_ctrl:1
	s_nop 1
	v_add_f32_dpp v4, v4, v4 row_shr:2 row_mask:0xf bank_mask:0xf bound_ctrl:1
	s_nop 1
	v_add_f32_dpp v4, v4, v4 row_shr:4 row_mask:0xf bank_mask:0xf bound_ctrl:1
	s_nop 1
	v_add_f32_dpp v4, v4, v4 row_shr:8 row_mask:0xf bank_mask:0xf bound_ctrl:1
	s_waitcnt lgkmcnt(7)
; #define LAS __attribute__((address_space(3)))
; __device__ __forceinline__ u32x4 pack8(const float (&v)[8]) { u32x4 w; w.x = pk2(v[0], v[1]); w.y = pk2(v[2], v[3]); w.z = pk2(v[4], v[5]); w.w = pk2(v[6], v[7]); return w; }
; __device__ __forceinline__ void ld8bf(const bf16_t* p, float (&o)[8]) { unpack8(*(const u32x4*)p, o); }
; __device__ __forceinline__ float row_sum_incl(float v) { v += dpp_shr0<1>(v); v += dpp_shr0<2>(v); v += dpp_shr0<4>(v); v += dpp_shr0<8>(v); return v; }
; __device__ __forceinline__ float bcast15(float v, int lane) { return bperm_f((lane & 48) | 15, v); }
; __device__ __forceinline__ void w_hg_scan(const float (&lbv)[8], const bf16_t* fsrc, int lane, float (&bb)[4][8], float (&r31)[8], float (&r63)[8]) {
;     ...
;     for (int tb = 0; tb < 4; ++tb) {
; #pragma unroll
;         for (int j = 0; j < 8; ++j) { const float v = row_sum_incl(bb[tb][j]) + carry[j]; bb[tb][j] = v; carry[j] = bcast15(v, lane); if (tb == 1) r31[j] = carry[j]; if (tb == 3) r63[j] = carry[j]; }
;         __builtin_amdgcn_sched_barrier(0);
;     }
; }
; __device__ __forceinline__ void w_hg_m1(const Args& a, int l, unsigned char* ws, const bf16_t* proj, LAS unsigned char* wl, int b, int ck_, int h, int lane) {
;     LAS bf16_t* vT = (LAS bf16_t*)wl; LAS bf16_t* kT = (LAS bf16_t*)(wl + TILE_B);
;     const int row0 = b * SEQ + 64 * ck_, lo = lane & 15, fq = lane >> 4;
; #pragma unroll
;     for (int kk = 0; kk < 2; ++kk) { float bb[4][8], r31[8], r63[8], lbv[8];
; #pragma unroll
;         for (int j = 0; j < 8; ++j) lbv[j] = hg_lb(a, l, 64 * h + 32 * kk + 8 * fq + j);
;         const bf16_t* fsrc = proj + (size_t)row0 * NIN + C_HF + 64 * h + 32 * kk + 8 * fq;
;         w_hg_scan(lbv, fsrc, lane, bb, r31, r63);
; #pragma unroll
;         for (int tb = 0; tb < 4; ++tb) { float fp[8]; ld8bf(fsrc + (size_t)(16 * tb + lo) * NIN, fp);
;             float kb[8];
; #pragma unroll
;             for (int j = 0; j < 8; ++j) { float lf, key; hg_lf_key(fp[j], lbv[j], lf, key); kb[j] = key * __expf(r63[j] - bb[tb][j]); }
;             *(LAS u32x4*)(kT + (16 * tb + lo) * LD + 32 * kk + 8 * fq) = pack8(kb); }
	v_add_f32_e32 v46, v4, v39
	ds_bpermute_b32 v39, v30, v46
	v_add_f32_dpp v4, v38, v38 row_shr:1 row_mask:0xf bank_mask:0xf bound_ctrl:1
	s_nop 1
	v_add_f32_dpp v4, v4, v4 row_shr:2 row_mask:0xf bank_mask:0xf bound_ctrl:1
	s_nop 1
	v_add_f32_dpp v4, v4, v4 row_shr:4 row_mask:0xf bank_mask:0xf bound_ctrl:1
	s_nop 1
	v_add_f32_dpp v4, v4, v4 row_shr:8 row_mask:0xf bank_mask:0xf bound_ctrl:1
	s_waitcnt lgkmcnt(7)
	v_add_f32_e32 v45, v4, v41
	ds_bpermute_b32 v36, v30, v45
	v_add_f32_dpp v4, v6, v6 row_shr:1 row_mask:0xf bank_mask:0xf bound_ctrl:1
	s_nop 1
	v_add_f32_dpp v4, v4, v4 row_shr:2 row_mask:0xf bank_mask:0xf bound_ctrl:1
	s_nop 1
	v_add_f32_dpp v4, v4, v4 row_shr:4 row_mask:0xf bank_mask:0xf bound_ctrl:1
	s_nop 1
	v_add_f32_dpp v4, v4, v4 row_shr:8 row_mask:0xf bank_mask:0xf bound_ctrl:1
	s_waitcnt lgkmcnt(7)
	v_add_f32_e32 v44, v4, v42
	ds_bpermute_b32 v38, v30, v44
	v_add_f32_dpp v4, v40, v40 row_shr:1 row_mask:0xf bank_mask:0xf bound_ctrl:1
	s_nop 1
	v_add_f32_dpp v4, v4, v4 row_shr:2 row_mask:0xf bank_mask:0xf bound_ctrl:1
	s_nop 1
	v_add_f32_dpp v4, v4, v4 row_shr:4 row_mask:0xf bank_mask:0xf bound_ctrl:1
	s_nop 1
	v_add_f32_dpp v4, v4, v4 row_shr:8 row_mask:0xf bank_mask:0xf bound_ctrl:1
	s_waitcnt lgkmcnt(7)
	v_add_f32_e32 v43, v4, v43
	ds_bpermute_b32 v40, v30, v43
	v_add_f32_dpp v4, v7, v7 row_shr:1 row_mask:0xf bank_mask:0xf bound_ctrl:1
	s_nop 1
	v_add_f32_dpp v4, v4, v4 row_shr:2 row_mask:0xf bank_mask:0xf bound_ctrl:1
	s_nop 1
	v_add_f32_dpp v4, v4, v4 row_shr:4 row_mask:0xf bank_mask:0xf bound_ctrl:1
	s_nop 1
	v_add_f32_dpp v4, v4, v4 row_shr:8 row_mask:0xf bank_mask:0xf bound_ctrl:1
	s_waitcnt lgkmcnt(7)
	v_add_f32_e32 v42, v4, v58
	ds_bpermute_b32 v41, v30, v42
	v_mov_b64_e32 v[4:5], v[238:239]
	v_mov_b64_e32 v[6:7], v[240:241]
	s_waitcnt lgkmcnt(0)
	v_sub_f32_e32 v30, v37, v73
	v_sub_f32_e32 v26, v39, v26
	v_sub_f32_e32 v27, v36, v27
	v_pk_add_f32 v[14:15], v[20:21], 1.0 op_sel_hi:[1,0] neg_lo:[1,0] neg_hi:[1,0]
	v_sub_f32_e32 v20, v1, v71
	v_sub_f32_e32 v28, v38, v28
	v_sub_f32_e32 v29, v40, v29
	v_mul_f32_e32 v30, 0x3fb8aa3b, v30
	v_mul_f32_e32 v58, 0x3fb8aa3b, v26
	v_mul_f32_e32 v61, 0x3fb8aa3b, v27
	v_sub_f32_e32 v31, v41, v31
	v_mul_f32_e32 v20, 0x3fb8aa3b, v20
	v_mul_f32_e32 v64, 0x3fb8aa3b, v28
	v_mul_f32_e32 v67, 0x3fb8aa3b, v29
	v_exp_f32_e32 v28, v30
	v_exp_f32_e32 v29, v58
	v_exp_f32_e32 v30, v61
	v_sub_f32_e32 v21, v35, v72
	v_mul_f32_e32 v71, 0x3fb8aa3b, v31
	v_exp_f32_e32 v26, v20
	v_exp_f32_e32 v31, v64
	v_exp_f32_e32 v20, v67
	v_mul_f32_e32 v21, 0x3fb8aa3b, v21
	v_exp_f32_e32 v27, v21
	v_exp_f32_e32 v21, v71
	v_pk_add_f32 v[18:19], v[18:19], 1.0 op_sel_hi:[1,0] neg_lo:[1,0] neg_hi:[1,0]
	v_pk_add_f32 v[16:17], v[16:17], 1.0 op_sel_hi:[1,0] neg_lo:[1,0] neg_hi:[1,0]
	v_add_u32_e32 v2, v2, v68
	s_waitcnt vmcnt(0)
	v_lshlrev_b32_e32 v58, 16, v4
	v_and_b32_e32 v61, 0xffff0000, v4
	v_lshlrev_b32_e32 v64, 16, v5
	v_and_b32_e32 v67, 0xffff0000, v5
	v_mul_f32_e64 v4, |v58|, s26
	v_mul_f32_e64 v5, |v61|, s26
	v_exp_f32_e32 v4, v4
	v_exp_f32_e32 v5, v5
	v_lshlrev_b32_e32 v71, 16, v6
	v_and_b32_e32 v84, 0xffff0000, v6
	v_lshlrev_b32_e32 v85, 16, v7
	v_and_b32_e32 v86, 0xffff0000, v7
	v_mul_f32_e64 v6, |v64|, s26
	v_mul_f32_e64 v7, |v67|, s26
	v_exp_f32_e32 v6, v6
	v_exp_f32_e32 v7, v7
	v_mul_f32_e64 v72, |v71|, s26
	v_mul_f32_e64 v73, |v84|, s26
	v_exp_f32_e32 v72, v72
	v_exp_f32_e32 v73, v73
	v_add_f32_e32 v76, 1.0, v4
	v_add_f32_e32 v77, 1.0, v5
	v_mul_f32_e64 v74, |v85|, s26
	v_mul_f32_e64 v75, |v86|, s26
	v_rcp_f32_e32 v76, v76
	v_rcp_f32_e32 v77, v77
	v_exp_f32_e32 v74, v74
	v_exp_f32_e32 v75, v75
	v_add_f32_e32 v78, 1.0, v6
	v_add_f32_e32 v79, 1.0, v7
	v_rcp_f32_e32 v78, v78
	v_rcp_f32_e32 v79, v79
	v_add_f32_e32 v80, 1.0, v72
	v_add_f32_e32 v81, 1.0, v73
	v_rcp_f32_e32 v80, v80
	v_rcp_f32_e32 v81, v81
	v_pk_mul_f32 v[4:5], v[4:5], v[76:77]
	v_cmp_le_f32_e32 vcc, 0, v61
	v_add_f32_e32 v82, 1.0, v74
	v_add_f32_e32 v83, 1.0, v75
	v_cndmask_b32_e32 v5, v77, v5, vcc
	v_cmp_le_f32_e32 vcc, 0, v58
	v_rcp_f32_e32 v82, v82
	v_rcp_f32_e32 v83, v83
	v_pk_mul_f32 v[6:7], v[6:7], v[78:79]
	v_cndmask_b32_e32 v4, v76, v4, vcc
	v_cmp_le_f32_e32 vcc, 0, v67
	v_pk_mul_f32 v[72:73], v[72:73], v[80:81]
	v_pk_mul_f32 v[74:75], v[74:75], v[82:83]
	v_cndmask_b32_e32 v7, v79, v7, vcc
	v_cmp_le_f32_e32 vcc, 0, v64
	v_pk_mul_f32 v[4:5], v[14:15], v[4:5]
	s_nop 0
	v_cndmask_b32_e32 v6, v78, v6, vcc
	v_cmp_le_f32_e32 vcc, 0, v84
	v_pk_mul_f32 v[6:7], v[18:19], v[6:7]
	v_pk_mul_f32 v[4:5], v[26:27], v[4:5]
	v_cndmask_b32_e32 v73, v81, v73, vcc
	v_cmp_le_f32_e32 vcc, 0, v71
	v_pk_mul_f32 v[6:7], v[28:29], v[6:7]
	v_cvt_pk_bf16_f32 v4, v4, v5
	v_cndmask_b32_e32 v72, v80, v72, vcc
	v_cmp_le_f32_e32 vcc, 0, v86
	v_pk_mul_f32 v[72:73], v[16:17], v[72:73]
	v_cvt_pk_bf16_f32 v5, v6, v7
	v_cndmask_b32_e32 v75, v83, v75, vcc
	v_cmp_le_f32_e32 vcc, 0, v85
	v_pk_mul_f32 v[26:27], v[30:31], v[72:73]
	v_sub_f32_e32 v28, v40, v60
	v_cndmask_b32_e32 v74, v82, v74, vcc
	v_pk_mul_f32 v[74:75], v[12:13], v[74:75]
	v_cvt_pk_bf16_f32 v6, v26, v27
	v_pk_mul_f32 v[20:21], v[20:21], v[74:75]
	v_sub_f32_e32 v26, v36, v63
	v_cvt_pk_bf16_f32 v7, v20, v21
	ds_write_b128 v2, v[4:7] offset:9280
	v_mov_b64_e32 v[4:5], v[242:243]
	v_mov_b64_e32 v[6:7], v[244:245]
	v_sub_f32_e32 v11, v35, v69
	v_sub_f32_e32 v10, v1, v70
	v_sub_f32_e32 v20, v37, v66
	v_sub_f32_e32 v21, v39, v65
	v_sub_f32_e32 v27, v38, v62
	v_sub_f32_e32 v29, v41, v59
	v_mul_f32_e32 v30, 0x3fb8aa3b, v20
	v_mul_f32_e32 v31, 0x3fb8aa3b, v21
	v_mul_f32_e32 v10, 0x3fb8aa3b, v10
	v_mul_f32_e32 v11, 0x3fb8aa3b, v11
	v_mul_f32_e32 v58, 0x3fb8aa3b, v26
	v_mul_f32_e32 v59, 0x3fb8aa3b, v27
	v_mul_f32_e32 v60, 0x3fb8aa3b, v28
	v_mul_f32_e32 v61, 0x3fb8aa3b, v29
	v_exp_f32_e32 v26, v30
	v_exp_f32_e32 v27, v31
	v_exp_f32_e32 v20, v10
	v_exp_f32_e32 v21, v11
	v_exp_f32_e32 v10, v60
	v_exp_f32_e32 v11, v61
	v_exp_f32_e32 v28, v58
	v_exp_f32_e32 v29, v59
	s_waitcnt vmcnt(0) lgkmcnt(0)
; #define LAS __attribute__((address_space(3)))
; __device__ __forceinline__ u32x4 pack8(const float (&v)[8]) { u32x4 w; w.x = pk2(v[0], v[1]); w.y = pk2(v[2], v[3]); w.z = pk2(v[4], v[5]); w.w = pk2(v[6], v[7]); return w; }
; __device__ __forceinline__ void ld8bf(const bf16_t* p, float (&o)[8]) { unpack8(*(const u32x4*)p, o); }
; __device__ __forceinline__ void hg_lf_key(float fp, float lb, float& lf, float& key) {
;     const float e = __expf(-fabsf(fp));
;     const float rc = __builtin_amdgcn_rcpf(1.0f + e);
;     const float sp = fp >= 0.f ? rc : e * rc;
;     const float sn = fp >= 0.f ? e * rc : rc;
;     const float lsig = (fp >= 0.f ? 0.f : fp) + __logf(rc);
;     lf = (lb == 0.f) ? lsig : __logf(lb + (1.0f - lb) * sp); key = (1.0f - lb) * sn;
; }
; __device__ __forceinline__ void w_hg_m1(const Args& a, int l, unsigned char* ws, const bf16_t* proj, LAS unsigned char* wl, int b, int ck_, int h, int lane) {
;     ...
;         for (int tb = 0; tb < 4; ++tb) { float fp[8]; ld8bf(fsrc + (size_t)(16 * tb + lo) * NIN, fp);
;             float kb[8];
; #pragma unroll
;             for (int j = 0; j < 8; ++j) { float lf, key; hg_lf_key(fp[j], lbv[j], lf, key); kb[j] = key * __expf(r63[j] - bb[tb][j]); }
;             *(LAS u32x4*)(kT + (16 * tb + lo) * LD + 32 * kk + 8 * fq) = pack8(kb); }
	v_lshlrev_b32_e32 v68, 16, v4
	v_and_b32_e32 v69, 0xffff0000, v4
	v_lshlrev_b32_e32 v70, 16, v5
	v_and_b32_e32 v71, 0xffff0000, v5
	v_mul_f32_e64 v4, |v68|, s26
	v_mul_f32_e64 v5, |v69|, s26
	v_exp_f32_e32 v4, v4
	v_exp_f32_e32 v5, v5
	v_lshlrev_b32_e32 v72, 16, v6
	v_and_b32_e32 v73, 0xffff0000, v6
	v_lshlrev_b32_e32 v74, 16, v7
	v_and_b32_e32 v75, 0xffff0000, v7
	v_mul_f32_e64 v6, |v70|, s26
	v_mul_f32_e64 v7, |v71|, s26
	v_exp_f32_e32 v6, v6
	v_exp_f32_e32 v7, v7
	v_mul_f32_e64 v30, |v72|, s26
	v_mul_f32_e64 v31, |v73|, s26
	v_exp_f32_e32 v30, v30
	v_exp_f32_e32 v31, v31
	v_add_f32_e32 v60, 1.0, v4
	v_add_f32_e32 v61, 1.0, v5
	v_mul_f32_e64 v58, |v74|, s26
	v_mul_f32_e64 v59, |v75|, s26
	v_rcp_f32_e32 v60, v60
	v_rcp_f32_e32 v61, v61
	v_exp_f32_e32 v58, v58
	v_exp_f32_e32 v59, v59
	v_add_f32_e32 v62, 1.0, v6
	v_add_f32_e32 v63, 1.0, v7
	v_rcp_f32_e32 v62, v62
	v_rcp_f32_e32 v63, v63
	v_add_f32_e32 v64, 1.0, v30
	v_add_f32_e32 v65, 1.0, v31
	v_rcp_f32_e32 v64, v64
	v_rcp_f32_e32 v65, v65
	v_pk_mul_f32 v[4:5], v[4:5], v[60:61]
	v_cmp_le_f32_e32 vcc, 0, v69
	v_add_f32_e32 v66, 1.0, v58
	v_add_f32_e32 v67, 1.0, v59
	v_cndmask_b32_e32 v5, v61, v5, vcc
	v_cmp_le_f32_e32 vcc, 0, v68
	v_rcp_f32_e32 v66, v66
	v_rcp_f32_e32 v67, v67
	v_pk_mul_f32 v[6:7], v[6:7], v[62:63]
	v_cndmask_b32_e32 v4, v60, v4, vcc
	v_cmp_le_f32_e32 vcc, 0, v71
	v_pk_mul_f32 v[30:31], v[30:31], v[64:65]
	v_pk_mul_f32 v[58:59], v[58:59], v[66:67]
	v_cndmask_b32_e32 v7, v63, v7, vcc
	v_cmp_le_f32_e32 vcc, 0, v70
	v_pk_mul_f32 v[4:5], v[14:15], v[4:5]
	s_nop 0
	v_cndmask_b32_e32 v6, v62, v6, vcc
	v_cmp_le_f32_e32 vcc, 0, v73
	v_pk_mul_f32 v[6:7], v[18:19], v[6:7]
	v_pk_mul_f32 v[4:5], v[20:21], v[4:5]
	v_cndmask_b32_e32 v31, v65, v31, vcc
	v_cmp_le_f32_e32 vcc, 0, v72
	v_pk_mul_f32 v[6:7], v[26:27], v[6:7]
	v_cvt_pk_bf16_f32 v4, v4, v5
	v_cndmask_b32_e32 v30, v64, v30, vcc
	v_cmp_le_f32_e32 vcc, 0, v75
	v_pk_mul_f32 v[30:31], v[16:17], v[30:31]
	v_cvt_pk_bf16_f32 v5, v6, v7
	v_cndmask_b32_e32 v59, v67, v59, vcc
	v_cmp_le_f32_e32 vcc, 0, v74
	v_pk_mul_f32 v[20:21], v[28:29], v[30:31]
	s_nop 0
	v_cndmask_b32_e32 v58, v66, v58, vcc
	v_pk_mul_f32 v[26:27], v[12:13], v[58:59]
	v_cvt_pk_bf16_f32 v6, v20, v21
	v_pk_mul_f32 v[10:11], v[10:11], v[26:27]
	v_sub_f32_e32 v20, v37, v55
	v_cvt_pk_bf16_f32 v7, v10, v11
	ds_write_b128 v2, v[4:7] offset:11584
	v_mov_b64_e32 v[4:5], v[246:247]
	v_mov_b64_e32 v[6:7], v[248:249]
	v_sub_f32_e32 v21, v39, v54
	v_sub_f32_e32 v10, v1, v57
	v_sub_f32_e32 v11, v35, v56
	v_sub_f32_e32 v24, v36, v53
	v_sub_f32_e32 v25, v38, v52
	v_sub_f32_e32 v26, v40, v51
	v_sub_f32_e32 v27, v41, v50
	v_mul_f32_e32 v28, 0x3fb8aa3b, v20
	v_mul_f32_e32 v29, 0x3fb8aa3b, v21
	v_mul_f32_e32 v10, 0x3fb8aa3b, v10
	v_mul_f32_e32 v11, 0x3fb8aa3b, v11
	v_mul_f32_e32 v30, 0x3fb8aa3b, v24
	v_mul_f32_e32 v31, 0x3fb8aa3b, v25
	v_mul_f32_e32 v50, 0x3fb8aa3b, v26
	v_mul_f32_e32 v51, 0x3fb8aa3b, v27
	v_exp_f32_e32 v24, v28
	v_exp_f32_e32 v25, v29
	v_exp_f32_e32 v20, v10
	v_exp_f32_e32 v21, v11
	v_exp_f32_e32 v10, v50
	v_exp_f32_e32 v11, v51
	v_exp_f32_e32 v26, v30
	v_exp_f32_e32 v27, v31
	s_waitcnt vmcnt(0) lgkmcnt(0)
; #define LAS __attribute__((address_space(3)))
; __device__ __forceinline__ u32x4 pack8(const float (&v)[8]) { u32x4 w; w.x = pk2(v[0], v[1]); w.y = pk2(v[2], v[3]); w.z = pk2(v[4], v[5]); w.w = pk2(v[6], v[7]); return w; }
; __device__ __forceinline__ void ld8bf(const bf16_t* p, float (&o)[8]) { unpack8(*(const u32x4*)p, o); }
; __device__ __forceinline__ void hg_lf_key(float fp, float lb, float& lf, float& key) {
;     const float e = __expf(-fabsf(fp));
;     const float rc = __builtin_amdgcn_rcpf(1.0f + e);
;     const float sp = fp >= 0.f ? rc : e * rc;
;     const float sn = fp >= 0.f ? e * rc : rc;
;     const float lsig = (fp >= 0.f ? 0.f : fp) + __logf(rc);
;     lf = (lb == 0.f) ? lsig : __logf(lb + (1.0f - lb) * sp); key = (1.0f - lb) * sn;
; }
; __device__ __forceinline__ void w_hg_m1(const Args& a, int l, unsigned char* ws, const bf16_t* proj, LAS unsigned char* wl, int b, int ck_, int h, int lane) {
;     ...
;         for (int tb = 0; tb < 4; ++tb) { float fp[8]; ld8bf(fsrc + (size_t)(16 * tb + lo) * NIN, fp);
;             float kb[8];
; #pragma unroll
;             for (int j = 0; j < 8; ++j) { float lf, key; hg_lf_key(fp[j], lbv[j], lf, key); kb[j] = key * __expf(r63[j] - bb[tb][j]); }
;             *(LAS u32x4*)(kT + (16 * tb + lo) * LD + 32 * kk + 8 * fq) = pack8(kb); }
;         if (lo == 0) { float* dp = (float*)(ws + WS_HGDEC) + (size_t)((b * NCH + ck_) * 4 + h) * 64 + 32 * kk + 8 * fq;
; #pragma unroll
;             for (int j = 0; j < 8; ++j) dp[j] = __expf(r63[j]); }
	v_lshlrev_b32_e32 v58, 16, v4
	v_and_b32_e32 v59, 0xffff0000, v4
	v_lshlrev_b32_e32 v60, 16, v5
	v_and_b32_e32 v61, 0xffff0000, v5
	v_mul_f32_e64 v4, |v58|, s26
	v_mul_f32_e64 v5, |v59|, s26
	v_exp_f32_e32 v4, v4
	v_exp_f32_e32 v5, v5
	v_lshlrev_b32_e32 v62, 16, v6
	v_and_b32_e32 v63, 0xffff0000, v6
	v_lshlrev_b32_e32 v64, 16, v7
	v_and_b32_e32 v65, 0xffff0000, v7
	v_mul_f32_e64 v6, |v60|, s26
	v_mul_f32_e64 v7, |v61|, s26
	v_exp_f32_e32 v6, v6
	v_exp_f32_e32 v7, v7
	v_mul_f32_e64 v28, |v62|, s26
	v_mul_f32_e64 v29, |v63|, s26
	v_exp_f32_e32 v28, v28
	v_exp_f32_e32 v29, v29
	v_add_f32_e32 v50, 1.0, v4
	v_add_f32_e32 v51, 1.0, v5
	v_mul_f32_e64 v30, |v64|, s26
	v_mul_f32_e64 v31, |v65|, s26
	v_rcp_f32_e32 v50, v50
	v_rcp_f32_e32 v51, v51
	v_exp_f32_e32 v30, v30
	v_exp_f32_e32 v31, v31
	v_add_f32_e32 v52, 1.0, v6
	v_add_f32_e32 v53, 1.0, v7
	v_rcp_f32_e32 v52, v52
	v_rcp_f32_e32 v53, v53
	v_add_f32_e32 v54, 1.0, v28
	v_add_f32_e32 v55, 1.0, v29
	v_rcp_f32_e32 v54, v54
	v_rcp_f32_e32 v55, v55
	v_pk_mul_f32 v[4:5], v[4:5], v[50:51]
	v_cmp_le_f32_e32 vcc, 0, v59
	v_add_f32_e32 v56, 1.0, v30
	v_add_f32_e32 v57, 1.0, v31
	v_cndmask_b32_e32 v5, v51, v5, vcc
	v_cmp_le_f32_e32 vcc, 0, v58
	v_rcp_f32_e32 v56, v56
	v_rcp_f32_e32 v57, v57
	v_pk_mul_f32 v[6:7], v[6:7], v[52:53]
	v_cndmask_b32_e32 v4, v50, v4, vcc
	v_cmp_le_f32_e32 vcc, 0, v61
	v_pk_mul_f32 v[28:29], v[28:29], v[54:55]
	v_pk_mul_f32 v[30:31], v[30:31], v[56:57]
	v_cndmask_b32_e32 v7, v53, v7, vcc
	v_cmp_le_f32_e32 vcc, 0, v60
	v_pk_mul_f32 v[4:5], v[14:15], v[4:5]
	s_nop 0
	v_cndmask_b32_e32 v6, v52, v6, vcc
	v_cmp_le_f32_e32 vcc, 0, v63
	v_pk_mul_f32 v[6:7], v[18:19], v[6:7]
	v_pk_mul_f32 v[4:5], v[20:21], v[4:5]
	v_cndmask_b32_e32 v29, v55, v29, vcc
	v_cmp_le_f32_e32 vcc, 0, v62
	v_pk_mul_f32 v[6:7], v[24:25], v[6:7]
	v_cvt_pk_bf16_f32 v4, v4, v5
	v_cndmask_b32_e32 v28, v54, v28, vcc
	v_cmp_le_f32_e32 vcc, 0, v65
	v_pk_mul_f32 v[28:29], v[16:17], v[28:29]
	v_cvt_pk_bf16_f32 v5, v6, v7
	v_cndmask_b32_e32 v31, v57, v31, vcc
	v_cmp_le_f32_e32 vcc, 0, v64
	v_pk_mul_f32 v[20:21], v[26:27], v[28:29]
	s_nop 0
	v_cndmask_b32_e32 v30, v56, v30, vcc
	v_pk_mul_f32 v[24:25], v[12:13], v[30:31]
	v_cvt_pk_bf16_f32 v6, v20, v21
	v_pk_mul_f32 v[10:11], v[10:11], v[24:25]
	v_sub_f32_e32 v20, v37, v47
	v_cvt_pk_bf16_f32 v7, v10, v11
	ds_write_b128 v2, v[4:7] offset:13888
	v_mov_b64_e32 v[4:5], v[250:251]
	v_mov_b64_e32 v[6:7], v[252:253]
	v_sub_f32_e32 v10, v1, v49
	v_sub_f32_e32 v11, v35, v48
	v_sub_f32_e32 v21, v39, v46
	v_sub_f32_e32 v22, v36, v45
	v_sub_f32_e32 v23, v38, v44
	v_sub_f32_e32 v24, v40, v43
	v_sub_f32_e32 v25, v41, v42
	v_mul_f32_e32 v26, 0x3fb8aa3b, v20
	v_mul_f32_e32 v27, 0x3fb8aa3b, v21
	v_mul_f32_e32 v10, 0x3fb8aa3b, v10
	v_mul_f32_e32 v11, 0x3fb8aa3b, v11
	v_mul_f32_e32 v28, 0x3fb8aa3b, v22
	v_mul_f32_e32 v29, 0x3fb8aa3b, v23
	v_mul_f32_e32 v30, 0x3fb8aa3b, v24
	v_mul_f32_e32 v31, 0x3fb8aa3b, v25
	v_exp_f32_e32 v22, v26
	v_exp_f32_e32 v23, v27
	v_exp_f32_e32 v20, v10
	v_exp_f32_e32 v21, v11
	v_exp_f32_e32 v10, v30
	v_exp_f32_e32 v11, v31
	v_exp_f32_e32 v24, v28
	v_exp_f32_e32 v25, v29
	s_waitcnt vmcnt(0) lgkmcnt(0)
	v_lshlrev_b32_e32 v48, 16, v4
	v_and_b32_e32 v49, 0xffff0000, v4
	v_lshlrev_b32_e32 v50, 16, v5
	v_and_b32_e32 v51, 0xffff0000, v5
	v_mul_f32_e64 v4, |v48|, s26
	v_mul_f32_e64 v5, |v49|, s26
	v_exp_f32_e32 v4, v4
	v_exp_f32_e32 v5, v5
	v_lshlrev_b32_e32 v52, 16, v6
	v_and_b32_e32 v53, 0xffff0000, v6
	v_lshlrev_b32_e32 v54, 16, v7
	v_and_b32_e32 v55, 0xffff0000, v7
	v_mul_f32_e64 v6, |v50|, s26
	v_mul_f32_e64 v7, |v51|, s26
	v_exp_f32_e32 v6, v6
	v_exp_f32_e32 v7, v7
	v_mul_f32_e64 v26, |v52|, s26
	v_mul_f32_e64 v27, |v53|, s26
	v_exp_f32_e32 v26, v26
	v_exp_f32_e32 v27, v27
	v_add_f32_e32 v30, 1.0, v4
	v_add_f32_e32 v31, 1.0, v5
	v_mul_f32_e64 v28, |v54|, s26
	v_mul_f32_e64 v29, |v55|, s26
	v_rcp_f32_e32 v30, v30
	v_rcp_f32_e32 v31, v31
	v_exp_f32_e32 v28, v28
	v_exp_f32_e32 v29, v29
	v_add_f32_e32 v42, 1.0, v6
	v_add_f32_e32 v43, 1.0, v7
	v_rcp_f32_e32 v42, v42
	v_rcp_f32_e32 v43, v43
	v_add_f32_e32 v44, 1.0, v26
	v_add_f32_e32 v45, 1.0, v27
	v_rcp_f32_e32 v44, v44
	v_rcp_f32_e32 v45, v45
	v_pk_mul_f32 v[4:5], v[4:5], v[30:31]
	v_cmp_le_f32_e32 vcc, 0, v49
	v_add_f32_e32 v46, 1.0, v28
	v_add_f32_e32 v47, 1.0, v29
	v_cndmask_b32_e32 v5, v31, v5, vcc
	v_cmp_le_f32_e32 vcc, 0, v48
	v_rcp_f32_e32 v46, v46
	v_rcp_f32_e32 v47, v47
	v_pk_mul_f32 v[6:7], v[6:7], v[42:43]
	v_cndmask_b32_e32 v4, v30, v4, vcc
	v_cmp_le_f32_e32 vcc, 0, v51
	v_pk_mul_f32 v[26:27], v[26:27], v[44:45]
	v_pk_mul_f32 v[28:29], v[28:29], v[46:47]
	v_cndmask_b32_e32 v7, v43, v7, vcc
	v_cmp_le_f32_e32 vcc, 0, v50
	v_pk_mul_f32 v[4:5], v[14:15], v[4:5]
	s_nop 0
	v_cndmask_b32_e32 v6, v42, v6, vcc
	v_cmp_le_f32_e32 vcc, 0, v53
	v_pk_mul_f32 v[6:7], v[18:19], v[6:7]
	v_pk_mul_f32 v[4:5], v[20:21], v[4:5]
	v_cndmask_b32_e32 v27, v45, v27, vcc
	v_cmp_le_f32_e32 vcc, 0, v52
	v_pk_mul_f32 v[6:7], v[22:23], v[6:7]
	v_cvt_pk_bf16_f32 v4, v4, v5
	v_cndmask_b32_e32 v26, v44, v26, vcc
	v_cmp_le_f32_e32 vcc, 0, v55
	v_pk_mul_f32 v[14:15], v[16:17], v[26:27]
	v_cvt_pk_bf16_f32 v5, v6, v7
	v_cndmask_b32_e32 v17, v47, v29, vcc
	v_cmp_le_f32_e32 vcc, 0, v54
	v_pk_mul_f32 v[14:15], v[24:25], v[14:15]
	s_nop 0
	v_cndmask_b32_e32 v16, v46, v28, vcc
	v_pk_mul_f32 v[12:13], v[12:13], v[16:17]
	v_cvt_pk_bf16_f32 v6, v14, v15
	v_pk_mul_f32 v[10:11], v[10:11], v[12:13]
	s_nop 0
	v_cvt_pk_bf16_f32 v7, v10, v11
	ds_write_b128 v2, v[4:7] offset:16192
	s_and_saveexec_b64 s[34:35], s[38:39]
	s_cbranch_execz .LBB0_529
	v_mul_f32_e32 v1, 0x3fb8aa3b, v1
	v_exp_f32_e32 v4, v1
	v_mul_f32_e32 v1, 0x3fb8aa3b, v35
	v_exp_f32_e32 v5, v1
	v_mul_f32_e32 v1, 0x3fb8aa3b, v37
	v_exp_f32_e32 v6, v1
	v_mul_f32_e32 v1, 0x3fb8aa3b, v39
	v_exp_f32_e32 v7, v1
	v_mul_f32_e32 v1, 0x3fb8aa3b, v36
	flat_store_dwordx4 v[8:9], v[4:7] offset:128
	s_nop 1
	v_exp_f32_e32 v4, v1
	v_mul_f32_e32 v1, 0x3fb8aa3b, v38
	v_exp_f32_e32 v5, v1
	v_mul_f32_e32 v1, 0x3fb8aa3b, v40
	v_exp_f32_e32 v6, v1
	v_mul_f32_e32 v1, 0x3fb8aa3b, v41
	v_exp_f32_e32 v7, v1
	flat_store_dwordx4 v[8:9], v[4:7] offset:144
	s_branch .LBB0_529
